# baseline + per-phase priority only (no stagger): softmax phase prio 1, MFMA phase prio 0
# baseline (speedup 1.0000x reference)
; #define SBAR() __builtin_amdgcn_sched_barrier(0)
; #define ATT_DMA_K(t) do { const bf16_t* kg_ = Kh + (size_t)(t) * 64 * LDK; LAS unsigned char* sb_ = lds + ((t) & 3) * KBUF; \
;     _Pragma("unroll") for (int i_ = 0; i_ < NKP; ++i_) __builtin_amdgcn_global_load_lds((const unsigned*)(kg_ + kgo[i_]), (LAS unsigned*)(sb_ + (wid + 8 * i_) * 1024), 16, 0, 0); } while (0)
; #define ATT_DMA_V(t, vs) do { const bf16_t* vg_ = Vh + (size_t)(t) * 64 * LDV; LAS unsigned char* sb_ = lds + V_OFF + (vs) * SHM_V; \
;     _Pragma("unroll") for (int i_ = 0; i_ < 2; ++i_) __builtin_amdgcn_global_load_lds((const unsigned*)(vg_ + vgo[i_]), (LAS unsigned*)(sb_ + (2 * wid + i_) * 1024), 16, 0, 0); } while (0)
; #define ATT_SEG(t) do { if constexpr (MODE != 0) { if (((t) == tL && tL > 0) || (t) == tR) { const float f_ = (t) == tR ? fR : fL; l_reg *= f_; \
;     _Pragma("unroll") for (int d = 0; d < 4; ++d) _Pragma("unroll") for (int r = 0; r < 16; ++r) o[d][r] *= f_; } } } while (0)
; #define ATT_TOP(N) do { asm volatile("s_waitcnt vmcnt(%0)" :: "n"(N) : "memory"); __builtin_amdgcn_s_barrier(); asm volatile("" ::: "memory"); } while (0)
; template <int DQK, int MODE, int LDQ, int LDK, int LDV> ...
;     ...
;     for (int j = 0; j < NT; ++j) {
;         if (j + 2 < NT) ATT_TOP(NKP + 2); else ATT_TOP(0);
;         if (j + 3 < NT) ATT_DMA_K(j + 3);
;         if (j + 2 < NT) ATT_DMA_V(j + 2, v2);
;         ATT_SEG(j); SBAR();
.LBB0_1920:
	s_and_b32 s1, s22, 0x6000
	s_add_i32 m0, s59, s1
	s_lshl_b32 s1, s96, 14
	s_waitcnt vmcnt(3)
	s_barrier
	s_add_i32 s1, s95, s1
	global_load_lds_dwordx4 v[100:101], off
	s_add_i32 s2, s1, 0x400
	s_mov_b32 m0, s1
	s_add_i32 s1, s62, s0
	global_load_lds_dwordx4 v[102:103], off
	s_mov_b32 m0, s2
	s_add_i32 s74, s6, s0
	global_load_lds_dwordx4 v[104:105], off
	s_cmp_eq_u32 s1, 1
	s_cselect_b64 s[2:3], -1, 0
	s_and_b64 vcc, s[4:5], s[2:3]
	s_cmp_eq_u32 s74, 1
	s_cselect_b64 s[2:3], -1, 0
	s_or_b64 vcc, s[2:3], vcc
	s_andn2_b64 vcc, exec, vcc
	s_mov_b32 s1, s23
	s_cbranch_vccnz .LBB0_1922
	v_cndmask_b32_e64 v122, v112, v113, s[2:3]
	v_pk_mul_f32 v[14:15], v[14:15], v[122:123] op_sel_hi:[1,0]
	v_pk_mul_f32 v[12:13], v[12:13], v[122:123] op_sel_hi:[1,0]
	v_pk_mul_f32 v[10:11], v[10:11], v[122:123] op_sel_hi:[1,0]
	v_pk_mul_f32 v[8:9], v[8:9], v[122:123] op_sel_hi:[1,0]
	v_pk_mul_f32 v[6:7], v[6:7], v[122:123] op_sel_hi:[1,0]
	v_pk_mul_f32 v[4:5], v[4:5], v[122:123] op_sel_hi:[1,0]
	v_pk_mul_f32 v[2:3], v[2:3], v[122:123] op_sel_hi:[1,0]
	v_pk_mul_f32 v[0:1], v[0:1], v[122:123] op_sel_hi:[1,0]
	v_pk_mul_f32 v[62:63], v[62:63], v[122:123] op_sel_hi:[1,0]
	v_pk_mul_f32 v[60:61], v[60:61], v[122:123] op_sel_hi:[1,0]
	v_pk_mul_f32 v[58:59], v[58:59], v[122:123] op_sel_hi:[1,0]
	v_pk_mul_f32 v[56:57], v[56:57], v[122:123] op_sel_hi:[1,0]
	v_pk_mul_f32 v[54:55], v[54:55], v[122:123] op_sel_hi:[1,0]
	v_pk_mul_f32 v[52:53], v[52:53], v[122:123] op_sel_hi:[1,0]
	v_pk_mul_f32 v[50:51], v[50:51], v[122:123] op_sel_hi:[1,0]
	v_pk_mul_f32 v[48:49], v[48:49], v[122:123] op_sel_hi:[1,0]
	v_pk_mul_f32 v[46:47], v[46:47], v[122:123] op_sel_hi:[1,0]
	v_pk_mul_f32 v[44:45], v[44:45], v[122:123] op_sel_hi:[1,0]
	v_pk_mul_f32 v[42:43], v[42:43], v[122:123] op_sel_hi:[1,0]
	v_pk_mul_f32 v[40:41], v[40:41], v[122:123] op_sel_hi:[1,0]
	v_pk_mul_f32 v[38:39], v[38:39], v[122:123] op_sel_hi:[1,0]
	v_pk_mul_f32 v[36:37], v[36:37], v[122:123] op_sel_hi:[1,0]
	v_pk_mul_f32 v[34:35], v[34:35], v[122:123] op_sel_hi:[1,0]
	v_pk_mul_f32 v[32:33], v[32:33], v[122:123] op_sel_hi:[1,0]
	v_pk_mul_f32 v[30:31], v[30:31], v[122:123] op_sel_hi:[1,0]
	v_pk_mul_f32 v[28:29], v[28:29], v[122:123] op_sel_hi:[1,0]
	v_pk_mul_f32 v[26:27], v[26:27], v[122:123] op_sel_hi:[1,0]
	v_pk_mul_f32 v[24:25], v[24:25], v[122:123] op_sel_hi:[1,0]
	v_pk_mul_f32 v[22:23], v[22:23], v[122:123] op_sel_hi:[1,0]
	v_pk_mul_f32 v[20:21], v[20:21], v[122:123] op_sel_hi:[1,0]
	v_pk_mul_f32 v[18:19], v[18:19], v[122:123] op_sel_hi:[1,0]
	v_pk_mul_f32 v[16:17], v[16:17], v[122:123] op_sel_hi:[1,0]
	v_mul_f32_e32 v120, v120, v122

; #define LAS __attribute__((address_space(3)))
; DI void expsum(f32x16& p, float& l_reg, bf16x8& pa0, bf16x8& pa1) {
; #pragma unroll
;     for (int r = 0; r < 16; ++r) p[r] = __builtin_amdgcn_exp2f(p[r]);
;     float ps = 0.f;
; #pragma unroll
;     for (int r = 0; r < 16; ++r) ps += p[r];
;     l_reg += ps; asm volatile("" : "+v"(l_reg));
;     ...
;     ATT_PK4(p, 0, pa0); ATT_PK4(p, 8, pa1);
;     ...
; }
; DI int v_rd_base(int lane) { return ((lane & 3) << 3) | (((lane >> 2) & 3) << 6) | (((lane >> 4) & 1) << 5) | (((lane >> 5) & 1) << 8); }
; template <int OFF> DI s16x4 tr_read(int vb) { s16x4 r; asm volatile("ds_read_b64_tr_b16 %0, %1 offset:%2" : "=&v"(r) : "v"(vb), "i"(OFF) : "memory"); return r; }
; template <int H> DI void v_reads(s16x4* vf, int vb) {
;     vf[0] = tr_read<v_rd_off(0, 2 * H, 0)>(vb); vf[1] = tr_read<v_rd_off(0, 2 * H, 1)>(vb); vf[2] = tr_read<v_rd_off(0, 2 * H + 1, 0)>(vb); vf[3] = tr_read<v_rd_off(0, 2 * H + 1, 1)>(vb);
;     vf[4] = tr_read<v_rd_off(1, 2 * H, 0)>(vb); vf[5] = tr_read<v_rd_off(1, 2 * H, 1)>(vb); vf[6] = tr_read<v_rd_off(1, 2 * H + 1, 0)>(vb); vf[7] = tr_read<v_rd_off(1, 2 * H + 1, 1)>(vb);
;     vf[8] = tr_read<v_rd_off(2, 2 * H, 0)>(vb); vf[9] = tr_read<v_rd_off(2, 2 * H, 1)>(vb); vf[10] = tr_read<v_rd_off(2, 2 * H + 1, 0)>(vb); vf[11] = tr_read<v_rd_off(2, 2 * H + 1, 1)>(vb);
;     vf[12] = tr_read<v_rd_off(3, 2 * H, 0)>(vb); vf[13] = tr_read<v_rd_off(3, 2 * H, 1)>(vb); vf[14] = tr_read<v_rd_off(3, 2 * H + 1, 0)>(vb); vf[15] = tr_read<v_rd_off(3, 2 * H + 1, 1)>(vb);
; }
; DI void pv_mma(f32x16* o, const s16x4* vf, bf16x8 pa0, bf16x8 pa1) {
;     ...
; #pragma unroll
;     for (int d0 = 0; d0 < 4; ++d0) {
;         o[d0] = __builtin_amdgcn_mfma_f32_32x32x16_bf16(pa0, ATT_PK(vf[4 * d0], vf[4 * d0 + 1]), o[d0], 0, 0, 0);
;         o[d0] = __builtin_amdgcn_mfma_f32_32x32x16_bf16(pa1, ATT_PK(vf[4 * d0 + 2], vf[4 * d0 + 3]), o[d0], 0, 0, 0); }
;     ...
; }
; template <int DQK, int D0A, int D0B> DI void k_reads(bf16x8* kf, const LAS unsigned char* Ks, int half, int r32, int hi) {
; #pragma unroll
;     for (int d0 = D0A; d0 < D0B; ++d0) kf[d0 - D0A] = *(const LAS bf16x8*)(Ks + half * (32 * DQK * 2) + kswz<DQK>(r32, (d0 * 16 + hi * 8) * 2));
; }
; template <int D0A, int D0B> DI void qk_mma(f32x16& p, const bf16x8* kf, const bf16x8* qr) {
; #pragma unroll
;     for (int d0 = D0A; d0 < D0B; ++d0) {
.LBB0_1924:
	s_add_i32 s3, s22, 0xffffc000
	s_and_b32 s3, s3, 0x6000
	v_add_u32_e32 v123, s3, v114
	v_add_u32_e32 v140, v123, v118
	v_add_u32_e32 v136, v123, v117
	v_add_u32_e32 v132, v123, v116
	v_add_u32_e32 v123, v123, v115
	ds_read_b128 v[124:127], v123
	ds_read_b128 v[132:135], v132
	ds_read_b128 v[136:139], v136
	ds_read_b128 v[140:143], v140
	ds_read_b64_tr_b16 v[144:145], v121 offset:0x2000
	ds_read_b64_tr_b16 v[146:147], v121 offset:0x2800
	ds_read_b64_tr_b16 v[148:149], v121 offset:0x3000
	ds_read_b64_tr_b16 v[150:151], v121 offset:0x3800
	ds_read_b64_tr_b16 v[152:153], v121 offset:0x2200
	ds_read_b64_tr_b16 v[154:155], v121 offset:0x2a00
	ds_read_b64_tr_b16 v[156:157], v121 offset:0x3200
	ds_read_b64_tr_b16 v[158:159], v121 offset:0x3a00
	ds_read_b64_tr_b16 v[162:163], v121 offset:0x2400
	ds_read_b64_tr_b16 v[164:165], v121 offset:0x2c00
	ds_read_b64_tr_b16 v[166:167], v121 offset:0x3400
	ds_read_b64_tr_b16 v[168:169], v121 offset:0x3c00
	ds_read_b64_tr_b16 v[170:171], v121 offset:0x2600
	ds_read_b64_tr_b16 v[172:173], v121 offset:0x2e00
	ds_read_b64_tr_b16 v[174:175], v121 offset:0x3600
	ds_read_b64_tr_b16 v[176:177], v121 offset:0x3e00
	s_setprio 1
	v_exp_f32_e32 v64, v64
	v_exp_f32_e32 v65, v65
	v_exp_f32_e32 v66, v66
	v_exp_f32_e32 v67, v67
	v_exp_f32_e32 v68, v68
	v_add_f32_e32 v121, 0, v64
	v_exp_f32_e32 v69, v69
	v_add_f32_e32 v121, v65, v121
	v_exp_f32_e32 v70, v70
	v_add_f32_e32 v121, v66, v121
	v_exp_f32_e32 v71, v71
	v_add_f32_e32 v121, v67, v121
	v_exp_f32_e32 v72, v72
	v_add_f32_e32 v121, v68, v121
	v_exp_f32_e32 v73, v73
	v_add_f32_e32 v121, v69, v121
	v_exp_f32_e32 v74, v74
	v_add_f32_e32 v121, v70, v121
	v_exp_f32_e32 v75, v75
	v_add_f32_e32 v121, v71, v121
	v_exp_f32_e32 v76, v76
	v_add_f32_e32 v121, v72, v121
	v_exp_f32_e32 v77, v77
	v_add_f32_e32 v121, v73, v121
	v_exp_f32_e32 v78, v78
	v_add_f32_e32 v121, v74, v121
	v_exp_f32_e32 v79, v79
	v_add_f32_e32 v121, v75, v121
	v_add_f32_e32 v121, v76, v121
	v_add_f32_e32 v121, v77, v121
	v_add_f32_e32 v121, v78, v121
	v_add_f32_e32 v121, v79, v121
	v_add_f32_e32 v120, v120, v121
	v_cvt_pk_bf16_f32 v64, v64, v65
	v_cvt_pk_bf16_f32 v65, v66, v67
	v_cvt_pk_bf16_f32 v66, v68, v69
	v_cvt_pk_bf16_f32 v67, v70, v71
	v_cvt_pk_bf16_f32 v68, v72, v73
	v_cvt_pk_bf16_f32 v69, v74, v75
	v_cvt_pk_bf16_f32 v70, v76, v77
	v_cvt_pk_bf16_f32 v71, v78, v79
	s_nop 0
	v_permlane32_swap_b32_e32 v64, v66
	v_permlane32_swap_b32_e32 v65, v67
	v_permlane32_swap_b32_e32 v68, v70
	v_permlane32_swap_b32_e32 v69, v71
	s_waitcnt lgkmcnt(0)
	s_setprio 0
	v_mfma_f32_32x32x16_bf16 v[0:15], v[64:67], v[144:147], v[0:15]
	s_cmp_lt_i32 s0, s55
	s_cselect_b64 s[74:75], -1, 0
	s_cmp_ge_i32 s0, s97
	s_cselect_b64 vcc, -1, 0
	s_or_b64 s[74:75], s[74:75], vcc
	s_and_b64 vcc, exec, s[74:75]
	v_mfma_f32_32x32x16_bf16 v[48:63], v[64:67], v[152:155], v[48:63]
	v_mfma_f32_32x32x16_bf16 v[32:47], v[64:67], v[162:165], v[32:47]
	v_mfma_f32_32x32x16_bf16 v[16:31], v[64:67], v[170:173], v[16:31]
	v_mfma_f32_32x32x16_bf16 v[0:15], v[68:71], v[148:151], v[0:15]
	v_mfma_f32_32x32x16_bf16 v[48:63], v[68:71], v[156:159], v[48:63]
	v_mfma_f32_32x32x16_bf16 v[32:47], v[68:71], v[166:169], v[32:47]
	v_mfma_f32_32x32x16_bf16 v[16:31], v[68:71], v[174:177], v[16:31]
	s_waitcnt lgkmcnt(0)
	v_mfma_f32_32x32x16_bf16 v[64:79], v[124:127], v[92:95], 0
	v_mfma_f32_32x32x16_bf16 v[64:79], v[132:135], v[88:91], v[64:79]
	v_mfma_f32_32x32x16_bf16 v[64:79], v[136:139], v[84:87], v[64:79]
	v_mfma_f32_32x32x16_bf16 v[64:79], v[140:143], v[80:83], v[64:79]
	s_cbranch_vccnz .LBB0_1926
	v_add_u32_e32 v136, 0x28988, v122
	v_add_u32_e32 v138, 0x289a0, v122
	v_add_u32_e32 v140, 0x289a8, v122
	v_add_u32_e32 v123, 0x289c0, v122
	v_add_u32_e32 v124, 0x289c8, v122
	v_add_u32_e32 v126, 0x289e0, v122
	v_add_u32_e32 v132, 0x289e8, v122
	v_add_u32_e32 v121, 0x28980, v122
	ds_read2_b32 v[122:123], v123 offset1:1
	ds_read2_b32 v[124:125], v124 offset1:1
	ds_read2_b32 v[126:127], v126 offset1:1
	ds_read2_b32 v[132:133], v132 offset1:1
	ds_read2_b32 v[134:135], v121 offset1:1
	ds_read2_b32 v[136:137], v136 offset1:1
	ds_read2_b32 v[138:139], v138 offset1:1
	ds_read2_b32 v[140:141], v140 offset1:1
	s_waitcnt lgkmcnt(0)
	v_pk_add_f32 v[78:79], v[78:79], v[132:133]
	v_pk_add_f32 v[76:77], v[76:77], v[126:127]
	v_pk_add_f32 v[74:75], v[74:75], v[124:125]
	v_pk_add_f32 v[72:73], v[72:73], v[122:123]
	v_pk_add_f32 v[70:71], v[70:71], v[140:141]
	v_pk_add_f32 v[68:69], v[68:69], v[138:139]
	v_pk_add_f32 v[66:67], v[66:67], v[136:137]
	v_pk_add_f32 v[64:65], v[64:65], v[134:135]

; #define SBAR() __builtin_amdgcn_sched_barrier(0)
; #define ATT_DMA_K(t) do { const bf16_t* kg_ = Kh + (size_t)(t) * 64 * LDK; LAS unsigned char* sb_ = lds + ((t) & 3) * KBUF; \
;     _Pragma("unroll") for (int i_ = 0; i_ < NKP; ++i_) __builtin_amdgcn_global_load_lds((const unsigned*)(kg_ + kgo[i_]), (LAS unsigned*)(sb_ + (wid + 8 * i_) * 1024), 16, 0, 0); } while (0)
; #define ATT_DMA_V(t, vs) do { const bf16_t* vg_ = Vh + (size_t)(t) * 64 * LDV; LAS unsigned char* sb_ = lds + V_OFF + (vs) * SHM_V; \
;     _Pragma("unroll") for (int i_ = 0; i_ < 2; ++i_) __builtin_amdgcn_global_load_lds((const unsigned*)(vg_ + vgo[i_]), (LAS unsigned*)(sb_ + (2 * wid + i_) * 1024), 16, 0, 0); } while (0)
; #define ATT_SEG(t) do { if constexpr (MODE != 0) { if (((t) == tL && tL > 0) || (t) == tR) { const float f_ = (t) == tR ? fR : fL; l_reg *= f_; \
;     _Pragma("unroll") for (int d = 0; d < 4; ++d) _Pragma("unroll") for (int r = 0; r < 16; ++r) o[d][r] *= f_; } } } while (0)
; #define ATT_TOP(N) do { asm volatile("s_waitcnt vmcnt(%0)" :: "n"(N) : "memory"); __builtin_amdgcn_s_barrier(); asm volatile("" ::: "memory"); } while (0)
; template <int DQK, int MODE, int LDQ, int LDK, int LDV> ...
;     ...
;     for (int j = 0; j < NT; ++j) {
;         if (j + 2 < NT) ATT_TOP(NKP + 2); else ATT_TOP(0);
;         if (j + 3 < NT) ATT_DMA_K(j + 3);
;         if (j + 2 < NT) ATT_DMA_V(j + 2, v2);
;         ATT_SEG(j); SBAR();
.LBB0_1928:
	s_add_i32 s0, s95, s2
	s_add_i32 s1, s0, 0x400
	s_add_u32 s56, s56, 0xfc0000
	s_addc_u32 s57, s57, 0
	s_waitcnt vmcnt(3)
	s_barrier
	v_lshl_add_u64 v[96:97], v[96:97], 1, s[56:57]
	s_mov_b32 m0, s0
	v_lshl_add_u64 v[98:99], v[98:99], 1, s[56:57]
	global_load_lds_dwordx4 v[96:97], off
	s_mov_b32 m0, s1
	s_cmp_lg_u32 s55, 61
	global_load_lds_dwordx4 v[98:99], off
	s_cselect_b64 s[0:1], -1, 0
	s_cmp_eq_u32 s58, 61
	s_cselect_b64 s[2:3], -1, 0
	s_cmp_lg_u32 s58, 61
	s_cselect_b64 s[4:5], -1, 0
	s_and_b64 s[0:1], s[4:5], s[0:1]
	s_and_b64 vcc, exec, s[0:1]
	s_cbranch_vccnz .LBB0_1930
	v_cndmask_b32_e64 v96, v112, v113, s[2:3]
	v_pk_mul_f32 v[14:15], v[14:15], v[96:97] op_sel_hi:[1,0]
	v_pk_mul_f32 v[12:13], v[12:13], v[96:97] op_sel_hi:[1,0]
	v_pk_mul_f32 v[10:11], v[10:11], v[96:97] op_sel_hi:[1,0]
	v_pk_mul_f32 v[8:9], v[8:9], v[96:97] op_sel_hi:[1,0]
	v_pk_mul_f32 v[6:7], v[6:7], v[96:97] op_sel_hi:[1,0]
	v_pk_mul_f32 v[4:5], v[4:5], v[96:97] op_sel_hi:[1,0]
	v_pk_mul_f32 v[2:3], v[2:3], v[96:97] op_sel_hi:[1,0]
	v_pk_mul_f32 v[0:1], v[0:1], v[96:97] op_sel_hi:[1,0]
	v_pk_mul_f32 v[62:63], v[62:63], v[96:97] op_sel_hi:[1,0]
	v_pk_mul_f32 v[60:61], v[60:61], v[96:97] op_sel_hi:[1,0]
	v_pk_mul_f32 v[58:59], v[58:59], v[96:97] op_sel_hi:[1,0]
	v_pk_mul_f32 v[56:57], v[56:57], v[96:97] op_sel_hi:[1,0]
	v_pk_mul_f32 v[54:55], v[54:55], v[96:97] op_sel_hi:[1,0]
	v_pk_mul_f32 v[52:53], v[52:53], v[96:97] op_sel_hi:[1,0]
	v_pk_mul_f32 v[50:51], v[50:51], v[96:97] op_sel_hi:[1,0]
	v_pk_mul_f32 v[48:49], v[48:49], v[96:97] op_sel_hi:[1,0]
	v_pk_mul_f32 v[46:47], v[46:47], v[96:97] op_sel_hi:[1,0]
	v_pk_mul_f32 v[44:45], v[44:45], v[96:97] op_sel_hi:[1,0]
	v_pk_mul_f32 v[42:43], v[42:43], v[96:97] op_sel_hi:[1,0]
	v_pk_mul_f32 v[40:41], v[40:41], v[96:97] op_sel_hi:[1,0]
	v_pk_mul_f32 v[38:39], v[38:39], v[96:97] op_sel_hi:[1,0]
	v_pk_mul_f32 v[36:37], v[36:37], v[96:97] op_sel_hi:[1,0]
	v_pk_mul_f32 v[34:35], v[34:35], v[96:97] op_sel_hi:[1,0]
	v_pk_mul_f32 v[32:33], v[32:33], v[96:97] op_sel_hi:[1,0]
	v_pk_mul_f32 v[30:31], v[30:31], v[96:97] op_sel_hi:[1,0]
	v_pk_mul_f32 v[28:29], v[28:29], v[96:97] op_sel_hi:[1,0]
	v_pk_mul_f32 v[26:27], v[26:27], v[96:97] op_sel_hi:[1,0]
	v_pk_mul_f32 v[24:25], v[24:25], v[96:97] op_sel_hi:[1,0]
	v_pk_mul_f32 v[22:23], v[22:23], v[96:97] op_sel_hi:[1,0]
	v_pk_mul_f32 v[20:21], v[20:21], v[96:97] op_sel_hi:[1,0]
	v_pk_mul_f32 v[18:19], v[18:19], v[96:97] op_sel_hi:[1,0]
	v_pk_mul_f32 v[16:17], v[16:17], v[96:97] op_sel_hi:[1,0]
	v_mul_f32_e32 v120, v120, v96

; #define LAS __attribute__((address_space(3)))
; DI void expsum(f32x16& p, float& l_reg, bf16x8& pa0, bf16x8& pa1) {
; #pragma unroll
;     for (int r = 0; r < 16; ++r) p[r] = __builtin_amdgcn_exp2f(p[r]);
;     float ps = 0.f;
; #pragma unroll
;     for (int r = 0; r < 16; ++r) ps += p[r];
;     l_reg += ps; asm volatile("" : "+v"(l_reg));
;     ...
;     ATT_PK4(p, 0, pa0); ATT_PK4(p, 8, pa1);
;     ...
; }
; DI int v_rd_base(int lane) { return ((lane & 3) << 3) | (((lane >> 2) & 3) << 6) | (((lane >> 4) & 1) << 5) | (((lane >> 5) & 1) << 8); }
; template <int OFF> DI s16x4 tr_read(int vb) { s16x4 r; asm volatile("ds_read_b64_tr_b16 %0, %1 offset:%2" : "=&v"(r) : "v"(vb), "i"(OFF) : "memory"); return r; }
; template <int H> DI void v_reads(s16x4* vf, int vb) {
;     vf[0] = tr_read<v_rd_off(0, 2 * H, 0)>(vb); vf[1] = tr_read<v_rd_off(0, 2 * H, 1)>(vb); vf[2] = tr_read<v_rd_off(0, 2 * H + 1, 0)>(vb); vf[3] = tr_read<v_rd_off(0, 2 * H + 1, 1)>(vb);
;     vf[4] = tr_read<v_rd_off(1, 2 * H, 0)>(vb); vf[5] = tr_read<v_rd_off(1, 2 * H, 1)>(vb); vf[6] = tr_read<v_rd_off(1, 2 * H + 1, 0)>(vb); vf[7] = tr_read<v_rd_off(1, 2 * H + 1, 1)>(vb);
;     vf[8] = tr_read<v_rd_off(2, 2 * H, 0)>(vb); vf[9] = tr_read<v_rd_off(2, 2 * H, 1)>(vb); vf[10] = tr_read<v_rd_off(2, 2 * H + 1, 0)>(vb); vf[11] = tr_read<v_rd_off(2, 2 * H + 1, 1)>(vb);
;     vf[12] = tr_read<v_rd_off(3, 2 * H, 0)>(vb); vf[13] = tr_read<v_rd_off(3, 2 * H, 1)>(vb); vf[14] = tr_read<v_rd_off(3, 2 * H + 1, 0)>(vb); vf[15] = tr_read<v_rd_off(3, 2 * H + 1, 1)>(vb);
; }
; DI void pv_mma(f32x16* o, const s16x4* vf, bf16x8 pa0, bf16x8 pa1) {
;     ...
; #pragma unroll
;     for (int d0 = 0; d0 < 4; ++d0) {
;         o[d0] = __builtin_amdgcn_mfma_f32_32x32x16_bf16(pa0, ATT_PK(vf[4 * d0], vf[4 * d0 + 1]), o[d0], 0, 0, 0);
;         o[d0] = __builtin_amdgcn_mfma_f32_32x32x16_bf16(pa1, ATT_PK(vf[4 * d0 + 2], vf[4 * d0 + 3]), o[d0], 0, 0, 0); }
;     ...
; }
; template <int DQK, int D0A, int D0B> DI void k_reads(bf16x8* kf, const LAS unsigned char* Ks, int half, int r32, int hi) {
; #pragma unroll
;     for (int d0 = D0A; d0 < D0B; ++d0) kf[d0 - D0A] = *(const LAS bf16x8*)(Ks + half * (32 * DQK * 2) + kswz<DQK>(r32, (d0 * 16 + hi * 8) * 2));
; }
; template <int D0A, int D0B> DI void qk_mma(f32x16& p, const bf16x8* kf, const bf16x8* qr) {
; #pragma unroll
;     for (int d0 = D0A; d0 < D0B; ++d0) {
.LBB0_1932:
	s_movk_i32 s64, 0x70
	ds_read_b128 v[98:101], v107 offset:16384
	ds_read_b128 v[102:105], v108 offset:16384
	ds_read_b128 v[114:117], v109 offset:16384
	ds_read_b128 v[118:121], v110 offset:16384
	ds_read_b64_tr_b16 v[122:123], v96 offset:0x2000
	ds_read_b64_tr_b16 v[124:125], v96 offset:0x2800
	ds_read_b64_tr_b16 v[132:133], v96 offset:0x3000
	ds_read_b64_tr_b16 v[134:135], v96 offset:0x3800
	ds_read_b64_tr_b16 v[136:137], v96 offset:0x2200
	ds_read_b64_tr_b16 v[138:139], v96 offset:0x2a00
	ds_read_b64_tr_b16 v[140:141], v96 offset:0x3200
	ds_read_b64_tr_b16 v[142:143], v96 offset:0x3a00
	ds_read_b64_tr_b16 v[144:145], v96 offset:0x2400
	ds_read_b64_tr_b16 v[146:147], v96 offset:0x2c00
	ds_read_b64_tr_b16 v[148:149], v96 offset:0x3400
	ds_read_b64_tr_b16 v[150:151], v96 offset:0x3c00
	ds_read_b64_tr_b16 v[152:153], v96 offset:0x2600
	ds_read_b64_tr_b16 v[154:155], v96 offset:0x2e00
	ds_read_b64_tr_b16 v[156:157], v96 offset:0x3600
	ds_read_b64_tr_b16 v[158:159], v96 offset:0x3e00
	s_nop 5
	s_setprio 1
	v_exp_f32_e32 v64, v64
	v_exp_f32_e32 v65, v65
	v_exp_f32_e32 v66, v66
	v_exp_f32_e32 v67, v67
	v_exp_f32_e32 v68, v68
	v_add_f32_e32 v96, 0, v64
	v_exp_f32_e32 v69, v69
	v_add_f32_e32 v96, v65, v96
	v_exp_f32_e32 v70, v70
	v_add_f32_e32 v96, v66, v96
	v_exp_f32_e32 v71, v71
	v_add_f32_e32 v96, v67, v96
	v_exp_f32_e32 v72, v72
	v_add_f32_e32 v96, v68, v96
	v_exp_f32_e32 v73, v73
	v_add_f32_e32 v96, v69, v96
	v_exp_f32_e32 v74, v74
	v_add_f32_e32 v96, v70, v96
	v_exp_f32_e32 v75, v75
	v_add_f32_e32 v96, v71, v96
	v_exp_f32_e32 v76, v76
	v_add_f32_e32 v96, v72, v96
	v_exp_f32_e32 v77, v77
	v_add_f32_e32 v96, v73, v96
	v_exp_f32_e32 v78, v78
	v_add_f32_e32 v96, v74, v96
	v_exp_f32_e32 v79, v79
	v_add_f32_e32 v96, v75, v96
	v_add_f32_e32 v96, v76, v96
	v_add_f32_e32 v96, v77, v96
	v_add_f32_e32 v96, v78, v96
	v_add_f32_e32 v96, v79, v96
	v_add_f32_e32 v96, v97, v96
	v_cvt_pk_bf16_f32 v64, v64, v65
	v_cvt_pk_bf16_f32 v65, v66, v67
	v_cvt_pk_bf16_f32 v66, v68, v69
	v_cvt_pk_bf16_f32 v67, v70, v71
	v_cvt_pk_bf16_f32 v68, v72, v73
	v_cvt_pk_bf16_f32 v69, v74, v75
	v_cvt_pk_bf16_f32 v70, v76, v77
	v_cvt_pk_bf16_f32 v71, v78, v79
	s_nop 0
	v_permlane32_swap_b32_e32 v64, v66
	v_permlane32_swap_b32_e32 v65, v67
	v_permlane32_swap_b32_e32 v68, v70
	v_permlane32_swap_b32_e32 v69, v71
	s_waitcnt lgkmcnt(0)
	s_setprio 0
	v_mfma_f32_32x32x16_bf16 v[0:15], v[64:67], v[122:125], v[0:15]
	s_cmp_lt_i32 s55, 63
	s_cselect_b64 s[0:1], -1, 0
	s_cmp_gt_i32 s58, 62
	s_cselect_b64 s[2:3], -1, 0
	s_and_b64 s[0:1], s[0:1], s[2:3]
	v_cndmask_b32_e64 v97, 0, 1, s[0:1]
	v_cmp_ne_u32_e64 s[2:3], 1, v97
	v_mfma_f32_32x32x16_bf16 v[48:63], v[64:67], v[136:139], v[48:63]
	v_sub_u32_e32 v97, 0xf80, v111
	s_andn2_b64 vcc, exec, s[0:1]
	v_lshlrev_b32_e32 v97, 2, v97
	v_mfma_f32_32x32x16_bf16 v[32:47], v[64:67], v[144:147], v[32:47]
	v_mfma_f32_32x32x16_bf16 v[16:31], v[64:67], v[152:155], v[16:31]
	v_mfma_f32_32x32x16_bf16 v[0:15], v[68:71], v[132:135], v[0:15]
	v_mfma_f32_32x32x16_bf16 v[48:63], v[68:71], v[140:143], v[48:63]
	v_mfma_f32_32x32x16_bf16 v[32:47], v[68:71], v[148:151], v[32:47]
	v_mfma_f32_32x32x16_bf16 v[16:31], v[68:71], v[156:159], v[16:31]
	s_waitcnt lgkmcnt(0)
	v_mfma_f32_32x32x16_bf16 v[64:79], v[98:101], v[92:95], 0
	v_mfma_f32_32x32x16_bf16 v[64:79], v[102:105], v[88:91], v[64:79]
	v_mfma_f32_32x32x16_bf16 v[64:79], v[114:117], v[84:87], v[64:79]
	v_mfma_f32_32x32x16_bf16 v[64:79], v[118:121], v[80:83], v[64:79]
	s_cbranch_vccnz .LBB0_1934
	v_add3_u32 v120, s88, v97, v130
	ds_read2_b32 v[98:99], v120 offset0:240 offset1:241
	ds_read2_b32 v[100:101], v120 offset0:242 offset1:243
	ds_read2_b32 v[102:103], v120 offset0:248 offset1:249
	ds_read2_b32 v[104:105], v120 offset0:250 offset1:251
	ds_read2_b32 v[114:115], v120 offset0:224 offset1:225
	ds_read2_b32 v[116:117], v120 offset0:226 offset1:227
	ds_read2_b32 v[118:119], v120 offset0:232 offset1:233
	ds_read2_b32 v[120:121], v120 offset0:234 offset1:235
	s_waitcnt lgkmcnt(0)
	s_nop 0
	v_pk_add_f32 v[78:79], v[78:79], v[104:105]
	v_pk_add_f32 v[76:77], v[76:77], v[102:103]
	v_pk_add_f32 v[74:75], v[74:75], v[100:101]
	v_pk_add_f32 v[72:73], v[72:73], v[98:99]
	v_pk_add_f32 v[70:71], v[70:71], v[120:121]
	v_pk_add_f32 v[68:69], v[68:69], v[118:119]
	v_pk_add_f32 v[66:67], v[66:67], v[116:117]
	v_pk_add_f32 v[64:65], v[64:65], v[114:115]
.LBB0_1934:
	s_cmp_lg_u32 s55, 62
	s_cselect_b64 s[0:1], -1, 0
	s_cmp_eq_u32 s58, 62
	s_cselect_b64 s[4:5], -1, 0
	s_cmp_lg_u32 s58, 62
	s_waitcnt vmcnt(0)
	s_barrier
	s_cselect_b64 s[6:7], -1, 0
	s_and_b64 s[0:1], s[6:7], s[0:1]
	s_and_b64 vcc, exec, s[0:1]
	s_cbranch_vccnz .LBB0_1936
	v_cndmask_b32_e64 v98, v112, v113, s[4:5]
	v_pk_mul_f32 v[14:15], v[98:99], v[14:15] op_sel_hi:[0,1]
	v_pk_mul_f32 v[12:13], v[98:99], v[12:13] op_sel_hi:[0,1]
	v_pk_mul_f32 v[10:11], v[98:99], v[10:11] op_sel_hi:[0,1]
	v_pk_mul_f32 v[8:9], v[98:99], v[8:9] op_sel_hi:[0,1]
	v_pk_mul_f32 v[6:7], v[98:99], v[6:7] op_sel_hi:[0,1]
	v_pk_mul_f32 v[4:5], v[98:99], v[4:5] op_sel_hi:[0,1]
	v_pk_mul_f32 v[2:3], v[98:99], v[2:3] op_sel_hi:[0,1]
	v_pk_mul_f32 v[0:1], v[98:99], v[0:1] op_sel_hi:[0,1]
	v_pk_mul_f32 v[62:63], v[98:99], v[62:63] op_sel_hi:[0,1]
	v_pk_mul_f32 v[60:61], v[98:99], v[60:61] op_sel_hi:[0,1]
	v_pk_mul_f32 v[58:59], v[98:99], v[58:59] op_sel_hi:[0,1]
	v_pk_mul_f32 v[56:57], v[98:99], v[56:57] op_sel_hi:[0,1]
	v_pk_mul_f32 v[54:55], v[98:99], v[54:55] op_sel_hi:[0,1]
	v_pk_mul_f32 v[52:53], v[98:99], v[52:53] op_sel_hi:[0,1]
	v_pk_mul_f32 v[50:51], v[98:99], v[50:51] op_sel_hi:[0,1]
	v_pk_mul_f32 v[48:49], v[98:99], v[48:49] op_sel_hi:[0,1]
	v_pk_mul_f32 v[46:47], v[98:99], v[46:47] op_sel_hi:[0,1]
	v_pk_mul_f32 v[44:45], v[98:99], v[44:45] op_sel_hi:[0,1]
	v_pk_mul_f32 v[42:43], v[98:99], v[42:43] op_sel_hi:[0,1]
	v_pk_mul_f32 v[40:41], v[98:99], v[40:41] op_sel_hi:[0,1]
	v_pk_mul_f32 v[38:39], v[98:99], v[38:39] op_sel_hi:[0,1]
	v_pk_mul_f32 v[36:37], v[98:99], v[36:37] op_sel_hi:[0,1]
	v_pk_mul_f32 v[34:35], v[98:99], v[34:35] op_sel_hi:[0,1]
	v_pk_mul_f32 v[32:33], v[98:99], v[32:33] op_sel_hi:[0,1]
	v_pk_mul_f32 v[30:31], v[98:99], v[30:31] op_sel_hi:[0,1]
	v_pk_mul_f32 v[28:29], v[98:99], v[28:29] op_sel_hi:[0,1]
	v_pk_mul_f32 v[26:27], v[98:99], v[26:27] op_sel_hi:[0,1]
	v_pk_mul_f32 v[24:25], v[98:99], v[24:25] op_sel_hi:[0,1]
	v_pk_mul_f32 v[22:23], v[98:99], v[22:23] op_sel_hi:[0,1]
	v_pk_mul_f32 v[20:21], v[98:99], v[20:21] op_sel_hi:[0,1]
	v_pk_mul_f32 v[18:19], v[98:99], v[18:19] op_sel_hi:[0,1]
	v_pk_mul_f32 v[16:17], v[98:99], v[16:17] op_sel_hi:[0,1]
	v_mul_f32_e32 v96, v98, v96

; #define LAS __attribute__((address_space(3)))
; DI void expsum(f32x16& p, float& l_reg, bf16x8& pa0, bf16x8& pa1) {
; #pragma unroll
;     for (int r = 0; r < 16; ++r) p[r] = __builtin_amdgcn_exp2f(p[r]);
;     float ps = 0.f;
; #pragma unroll
;     for (int r = 0; r < 16; ++r) ps += p[r];
;     l_reg += ps; asm volatile("" : "+v"(l_reg));
;     ...
;     ATT_PK4(p, 0, pa0); ATT_PK4(p, 8, pa1);
;     ...
; }
; DI int v_rd_base(int lane) { return ((lane & 3) << 3) | (((lane >> 2) & 3) << 6) | (((lane >> 4) & 1) << 5) | (((lane >> 5) & 1) << 8); }
; template <int OFF> DI s16x4 tr_read(int vb) { s16x4 r; asm volatile("ds_read_b64_tr_b16 %0, %1 offset:%2" : "=&v"(r) : "v"(vb), "i"(OFF) : "memory"); return r; }
; template <int H> DI void v_reads(s16x4* vf, int vb) {
;     vf[0] = tr_read<v_rd_off(0, 2 * H, 0)>(vb); vf[1] = tr_read<v_rd_off(0, 2 * H, 1)>(vb); vf[2] = tr_read<v_rd_off(0, 2 * H + 1, 0)>(vb); vf[3] = tr_read<v_rd_off(0, 2 * H + 1, 1)>(vb);
;     vf[4] = tr_read<v_rd_off(1, 2 * H, 0)>(vb); vf[5] = tr_read<v_rd_off(1, 2 * H, 1)>(vb); vf[6] = tr_read<v_rd_off(1, 2 * H + 1, 0)>(vb); vf[7] = tr_read<v_rd_off(1, 2 * H + 1, 1)>(vb);
;     vf[8] = tr_read<v_rd_off(2, 2 * H, 0)>(vb); vf[9] = tr_read<v_rd_off(2, 2 * H, 1)>(vb); vf[10] = tr_read<v_rd_off(2, 2 * H + 1, 0)>(vb); vf[11] = tr_read<v_rd_off(2, 2 * H + 1, 1)>(vb);
;     vf[12] = tr_read<v_rd_off(3, 2 * H, 0)>(vb); vf[13] = tr_read<v_rd_off(3, 2 * H, 1)>(vb); vf[14] = tr_read<v_rd_off(3, 2 * H + 1, 0)>(vb); vf[15] = tr_read<v_rd_off(3, 2 * H + 1, 1)>(vb);
; }
; DI void pv_mma(f32x16* o, const s16x4* vf, bf16x8 pa0, bf16x8 pa1) {
;     ...
; #pragma unroll
;     for (int d0 = 0; d0 < 4; ++d0) {
;         o[d0] = __builtin_amdgcn_mfma_f32_32x32x16_bf16(pa0, ATT_PK(vf[4 * d0], vf[4 * d0 + 1]), o[d0], 0, 0, 0);
;         o[d0] = __builtin_amdgcn_mfma_f32_32x32x16_bf16(pa1, ATT_PK(vf[4 * d0 + 2], vf[4 * d0 + 3]), o[d0], 0, 0, 0); }
;     ...
; }
; template <int DQK, int D0A, int D0B> DI void k_reads(bf16x8* kf, const LAS unsigned char* Ks, int half, int r32, int hi) {
; #pragma unroll
;     for (int d0 = D0A; d0 < D0B; ++d0) kf[d0 - D0A] = *(const LAS bf16x8*)(Ks + half * (32 * DQK * 2) + kswz<DQK>(r32, (d0 * 16 + hi * 8) * 2));
; }
; template <int D0A, int D0B> DI void qk_mma(f32x16& p, const bf16x8* kf, const bf16x8* qr) {
; #pragma unroll
;     for (int d0 = D0A; d0 < D0B; ++d0) {
.LBB0_1938:
	ds_read_b128 v[100:103], v107 offset:24576
	ds_read_b128 v[114:117], v108 offset:24576
	ds_read_b128 v[118:121], v109 offset:24576
	ds_read_b128 v[122:125], v110 offset:24576
	ds_read_b64_tr_b16 v[132:133], v98 offset:0x2000
	ds_read_b64_tr_b16 v[134:135], v98 offset:0x2800
	ds_read_b64_tr_b16 v[136:137], v98 offset:0x3000
	ds_read_b64_tr_b16 v[138:139], v98 offset:0x3800
	ds_read_b64_tr_b16 v[140:141], v98 offset:0x2200
	ds_read_b64_tr_b16 v[142:143], v98 offset:0x2a00
	ds_read_b64_tr_b16 v[144:145], v98 offset:0x3200
	ds_read_b64_tr_b16 v[146:147], v98 offset:0x3a00
	ds_read_b64_tr_b16 v[148:149], v98 offset:0x2400
	ds_read_b64_tr_b16 v[150:151], v98 offset:0x2c00
	ds_read_b64_tr_b16 v[152:153], v98 offset:0x3400
	ds_read_b64_tr_b16 v[154:155], v98 offset:0x3c00
	ds_read_b64_tr_b16 v[156:157], v98 offset:0x2600
	ds_read_b64_tr_b16 v[158:159], v98 offset:0x2e00
	ds_read_b64_tr_b16 v[162:163], v98 offset:0x3600
	ds_read_b64_tr_b16 v[164:165], v98 offset:0x3e00
	s_nop 6
	s_setprio 1
	v_exp_f32_e32 v64, v64
	v_exp_f32_e32 v65, v65
	v_exp_f32_e32 v66, v66
	v_exp_f32_e32 v67, v67
	v_exp_f32_e32 v68, v68
	v_add_f32_e32 v97, 0, v64
	v_exp_f32_e32 v69, v69
	v_add_f32_e32 v97, v65, v97
	v_exp_f32_e32 v70, v70
	v_add_f32_e32 v97, v66, v97
	v_exp_f32_e32 v71, v71
	v_add_f32_e32 v97, v67, v97
	v_exp_f32_e32 v72, v72
	v_add_f32_e32 v97, v68, v97
	v_exp_f32_e32 v73, v73
	v_add_f32_e32 v97, v69, v97
	v_exp_f32_e32 v74, v74
	v_add_f32_e32 v97, v70, v97
	v_exp_f32_e32 v75, v75
	v_add_f32_e32 v97, v71, v97
	v_exp_f32_e32 v76, v76
	v_add_f32_e32 v97, v72, v97
	v_exp_f32_e32 v77, v77
	v_add_f32_e32 v97, v73, v97
	v_exp_f32_e32 v78, v78
	v_add_f32_e32 v97, v74, v97
	v_exp_f32_e32 v79, v79
	v_add_f32_e32 v97, v75, v97
	v_add_f32_e32 v97, v76, v97
	v_add_f32_e32 v97, v77, v97
	v_add_f32_e32 v97, v78, v97
	v_add_f32_e32 v97, v79, v97
	v_add_f32_e32 v96, v96, v97
	v_cvt_pk_bf16_f32 v64, v64, v65
	v_cvt_pk_bf16_f32 v65, v66, v67
	v_cvt_pk_bf16_f32 v66, v68, v69
	v_cvt_pk_bf16_f32 v67, v70, v71
	v_cvt_pk_bf16_f32 v68, v72, v73
	v_cvt_pk_bf16_f32 v69, v74, v75
	v_cvt_pk_bf16_f32 v70, v76, v77
	v_cvt_pk_bf16_f32 v71, v78, v79
	s_nop 0
	v_permlane32_swap_b32_e32 v64, v66
	v_permlane32_swap_b32_e32 v65, v67
	v_permlane32_swap_b32_e32 v68, v70
	v_permlane32_swap_b32_e32 v69, v71
	s_waitcnt lgkmcnt(0)
	s_setprio 0
	v_mfma_f32_32x32x16_bf16 v[0:15], v[64:67], v[132:135], v[0:15]
	s_cmp_lt_i32 s55, 64
	s_cselect_b64 s[0:1], -1, 0
	s_cmp_gt_i32 s58, 63
	s_cselect_b64 s[2:3], -1, 0
	s_and_b64 s[0:1], s[2:3], s[0:1]
	v_cndmask_b32_e64 v97, 0, 1, s[0:1]
	v_cmp_ne_u32_e64 s[2:3], 1, v97
	v_mfma_f32_32x32x16_bf16 v[48:63], v[64:67], v[140:143], v[48:63]
	v_sub_u32_e32 v97, 0xfc0, v111
	s_andn2_b64 vcc, exec, s[0:1]
	v_lshlrev_b32_e32 v97, 2, v97
	v_mfma_f32_32x32x16_bf16 v[32:47], v[64:67], v[148:151], v[32:47]
	v_mfma_f32_32x32x16_bf16 v[16:31], v[64:67], v[156:159], v[16:31]
	v_mfma_f32_32x32x16_bf16 v[0:15], v[68:71], v[136:139], v[0:15]
	v_mfma_f32_32x32x16_bf16 v[48:63], v[68:71], v[144:147], v[48:63]
	v_mfma_f32_32x32x16_bf16 v[32:47], v[68:71], v[152:155], v[32:47]
	v_mfma_f32_32x32x16_bf16 v[16:31], v[68:71], v[162:165], v[16:31]
	s_waitcnt lgkmcnt(0)
	v_mfma_f32_32x32x16_bf16 v[64:79], v[100:103], v[92:95], 0
	v_mfma_f32_32x32x16_bf16 v[64:79], v[114:117], v[88:91], v[64:79]
	v_mfma_f32_32x32x16_bf16 v[64:79], v[118:121], v[84:87], v[64:79]
	v_mfma_f32_32x32x16_bf16 v[64:79], v[122:125], v[80:83], v[64:79]
	s_cbranch_vccnz .LBB0_1940
	v_add3_u32 v111, s88, v97, v130
	ds_read2_b32 v[98:99], v111 offset0:240 offset1:241
	ds_read2_b32 v[100:101], v111 offset0:242 offset1:243
	ds_read2_b32 v[102:103], v111 offset0:248 offset1:249
	ds_read2_b32 v[104:105], v111 offset0:250 offset1:251
	ds_read2_b32 v[114:115], v111 offset0:224 offset1:225
	ds_read2_b32 v[116:117], v111 offset0:226 offset1:227
	ds_read2_b32 v[118:119], v111 offset0:232 offset1:233
	ds_read2_b32 v[120:121], v111 offset0:234 offset1:235
	s_waitcnt lgkmcnt(0)
	s_nop 0
	v_pk_add_f32 v[78:79], v[78:79], v[104:105]
	v_pk_add_f32 v[76:77], v[76:77], v[102:103]
	v_pk_add_f32 v[74:75], v[74:75], v[100:101]
	v_pk_add_f32 v[72:73], v[72:73], v[98:99]
	v_pk_add_f32 v[70:71], v[70:71], v[120:121]
	v_pk_add_f32 v[68:69], v[68:69], v[118:119]
	v_pk_add_f32 v[66:67], v[66:67], v[116:117]
	v_pk_add_f32 v[64:65], v[64:65], v[114:115]
.LBB0_1940:
	s_cmp_lg_u32 s55, 63
	s_cselect_b64 s[0:1], -1, 0
	s_cmp_eq_u32 s58, 63
	s_cselect_b64 s[4:5], -1, 0
	s_cmp_lg_u32 s58, 63
	s_waitcnt vmcnt(0)
	s_barrier
	s_cselect_b64 s[6:7], -1, 0
	s_and_b64 s[0:1], s[6:7], s[0:1]
	s_and_b64 vcc, exec, s[0:1]
	s_cbranch_vccnz .LBB0_1942
	v_cndmask_b32_e64 v98, v112, v113, s[4:5]
	v_pk_mul_f32 v[14:15], v[98:99], v[14:15] op_sel_hi:[0,1]
	v_pk_mul_f32 v[12:13], v[98:99], v[12:13] op_sel_hi:[0,1]
	v_pk_mul_f32 v[10:11], v[98:99], v[10:11] op_sel_hi:[0,1]
	v_pk_mul_f32 v[8:9], v[98:99], v[8:9] op_sel_hi:[0,1]
	v_pk_mul_f32 v[6:7], v[98:99], v[6:7] op_sel_hi:[0,1]
	v_pk_mul_f32 v[4:5], v[98:99], v[4:5] op_sel_hi:[0,1]
	v_pk_mul_f32 v[2:3], v[98:99], v[2:3] op_sel_hi:[0,1]
	v_pk_mul_f32 v[0:1], v[98:99], v[0:1] op_sel_hi:[0,1]
	v_pk_mul_f32 v[62:63], v[98:99], v[62:63] op_sel_hi:[0,1]
	v_pk_mul_f32 v[60:61], v[98:99], v[60:61] op_sel_hi:[0,1]
	v_pk_mul_f32 v[58:59], v[98:99], v[58:59] op_sel_hi:[0,1]
	v_pk_mul_f32 v[56:57], v[98:99], v[56:57] op_sel_hi:[0,1]
	v_pk_mul_f32 v[54:55], v[98:99], v[54:55] op_sel_hi:[0,1]
	v_pk_mul_f32 v[52:53], v[98:99], v[52:53] op_sel_hi:[0,1]
	v_pk_mul_f32 v[50:51], v[98:99], v[50:51] op_sel_hi:[0,1]
	v_pk_mul_f32 v[48:49], v[98:99], v[48:49] op_sel_hi:[0,1]
	v_pk_mul_f32 v[46:47], v[98:99], v[46:47] op_sel_hi:[0,1]
	v_pk_mul_f32 v[44:45], v[98:99], v[44:45] op_sel_hi:[0,1]
	v_pk_mul_f32 v[42:43], v[98:99], v[42:43] op_sel_hi:[0,1]
	v_pk_mul_f32 v[40:41], v[98:99], v[40:41] op_sel_hi:[0,1]
	v_pk_mul_f32 v[38:39], v[98:99], v[38:39] op_sel_hi:[0,1]
	v_pk_mul_f32 v[36:37], v[98:99], v[36:37] op_sel_hi:[0,1]
	v_pk_mul_f32 v[34:35], v[98:99], v[34:35] op_sel_hi:[0,1]
	v_pk_mul_f32 v[32:33], v[98:99], v[32:33] op_sel_hi:[0,1]
	v_pk_mul_f32 v[30:31], v[98:99], v[30:31] op_sel_hi:[0,1]
	v_pk_mul_f32 v[28:29], v[98:99], v[28:29] op_sel_hi:[0,1]
	v_pk_mul_f32 v[26:27], v[98:99], v[26:27] op_sel_hi:[0,1]
	v_pk_mul_f32 v[24:25], v[98:99], v[24:25] op_sel_hi:[0,1]
	v_pk_mul_f32 v[22:23], v[98:99], v[22:23] op_sel_hi:[0,1]
	v_pk_mul_f32 v[20:21], v[98:99], v[20:21] op_sel_hi:[0,1]
	v_pk_mul_f32 v[18:19], v[98:99], v[18:19] op_sel_hi:[0,1]
	v_pk_mul_f32 v[16:17], v[98:99], v[16:17] op_sel_hi:[0,1]
	v_mul_f32_e32 v96, v98, v96

; #define SBAR() __builtin_amdgcn_sched_barrier(0)
; #define ATT_DMA_K(t) do { const bf16_t* kg_ = Kh + (size_t)(t) * 64 * LDK; LAS unsigned char* sb_ = lds + ((t) & 3) * KBUF; \
;     _Pragma("unroll") for (int i_ = 0; i_ < NKP; ++i_) __builtin_amdgcn_global_load_lds((const unsigned*)(kg_ + kgo[i_]), (LAS unsigned*)(sb_ + (wid + 8 * i_) * 1024), 16, 0, 0); } while (0)
; #define ATT_DMA_V(t, vs) do { const bf16_t* vg_ = Vh + (size_t)(t) * 64 * LDV; LAS unsigned char* sb_ = lds + V_OFF + (vs) * SHM_V; \
;     _Pragma("unroll") for (int i_ = 0; i_ < 2; ++i_) __builtin_amdgcn_global_load_lds((const unsigned*)(vg_ + vgo[i_]), (LAS unsigned*)(sb_ + (2 * wid + i_) * 1024), 16, 0, 0); } while (0)
; #define ATT_SEG(t) do { if constexpr (MODE != 0) { if (((t) == tL && tL > 0) || (t) == tR) { const float f_ = (t) == tR ? fR : fL; l_reg *= f_; \
;     _Pragma("unroll") for (int d = 0; d < 4; ++d) _Pragma("unroll") for (int r = 0; r < 16; ++r) o[d][r] *= f_; } } } while (0)
; #define ATT_TOP(N) do { asm volatile("s_waitcnt vmcnt(%0)" :: "n"(N) : "memory"); __builtin_amdgcn_s_barrier(); asm volatile("" ::: "memory"); } while (0)
; template <int DQK, int MODE, int LDQ, int LDK, int LDV> ...
;     ...
;     for (int j = 0; j < NT; ++j) {
;         if (j + 2 < NT) ATT_TOP(NKP + 2); else ATT_TOP(0);
;         if (j + 3 < NT) ATT_DMA_K(j + 3);
;         if (j + 2 < NT) ATT_DMA_V(j + 2, v2);
;         ATT_SEG(j); SBAR();
.LBB0_1951:
	s_and_b32 s2, s22, 0x6000
	s_add_i32 m0, s94, s2
	s_lshl_b32 s2, s1, 14
	s_waitcnt vmcnt(3)
	s_barrier
	s_add_i32 s2, s48, s2
	global_load_lds_dwordx4 v[100:101], off
	s_add_i32 s3, s2, 0x400
	s_mov_b32 m0, s2
	s_add_i32 s2, s53, s0
	global_load_lds_dwordx4 v[102:103], off
	s_mov_b32 m0, s3
	s_add_i32 s23, s6, s0
	global_load_lds_dwordx4 v[104:105], off
	s_cmp_eq_u32 s2, 1
	s_cselect_b64 s[2:3], -1, 0
	s_and_b64 s[74:75], s[4:5], s[2:3]
	s_cmp_eq_u32 s23, 1
	s_cselect_b64 s[2:3], -1, 0
	s_or_b64 s[74:75], s[2:3], s[74:75]
	s_andn2_b64 vcc, exec, s[74:75]
	s_mov_b32 s23, s62
	s_cbranch_vccnz .LBB0_1953
	v_cndmask_b32_e64 v122, v112, v113, s[2:3]
	v_pk_mul_f32 v[14:15], v[14:15], v[122:123] op_sel_hi:[1,0]
	v_pk_mul_f32 v[12:13], v[12:13], v[122:123] op_sel_hi:[1,0]
	v_pk_mul_f32 v[10:11], v[10:11], v[122:123] op_sel_hi:[1,0]
	v_pk_mul_f32 v[8:9], v[8:9], v[122:123] op_sel_hi:[1,0]
	v_pk_mul_f32 v[6:7], v[6:7], v[122:123] op_sel_hi:[1,0]
	v_pk_mul_f32 v[4:5], v[4:5], v[122:123] op_sel_hi:[1,0]
	v_pk_mul_f32 v[2:3], v[2:3], v[122:123] op_sel_hi:[1,0]
	v_pk_mul_f32 v[0:1], v[0:1], v[122:123] op_sel_hi:[1,0]
	v_pk_mul_f32 v[62:63], v[62:63], v[122:123] op_sel_hi:[1,0]
	v_pk_mul_f32 v[60:61], v[60:61], v[122:123] op_sel_hi:[1,0]
	v_pk_mul_f32 v[58:59], v[58:59], v[122:123] op_sel_hi:[1,0]
	v_pk_mul_f32 v[56:57], v[56:57], v[122:123] op_sel_hi:[1,0]
	v_pk_mul_f32 v[54:55], v[54:55], v[122:123] op_sel_hi:[1,0]
	v_pk_mul_f32 v[52:53], v[52:53], v[122:123] op_sel_hi:[1,0]
	v_pk_mul_f32 v[50:51], v[50:51], v[122:123] op_sel_hi:[1,0]
	v_pk_mul_f32 v[48:49], v[48:49], v[122:123] op_sel_hi:[1,0]
	v_pk_mul_f32 v[30:31], v[30:31], v[122:123] op_sel_hi:[1,0]
	v_pk_mul_f32 v[28:29], v[28:29], v[122:123] op_sel_hi:[1,0]
	v_pk_mul_f32 v[26:27], v[26:27], v[122:123] op_sel_hi:[1,0]
	v_pk_mul_f32 v[24:25], v[24:25], v[122:123] op_sel_hi:[1,0]
	v_pk_mul_f32 v[22:23], v[22:23], v[122:123] op_sel_hi:[1,0]
	v_pk_mul_f32 v[20:21], v[20:21], v[122:123] op_sel_hi:[1,0]
	v_pk_mul_f32 v[18:19], v[18:19], v[122:123] op_sel_hi:[1,0]
	v_pk_mul_f32 v[16:17], v[16:17], v[122:123] op_sel_hi:[1,0]
	v_pk_mul_f32 v[46:47], v[46:47], v[122:123] op_sel_hi:[1,0]
	v_pk_mul_f32 v[44:45], v[44:45], v[122:123] op_sel_hi:[1,0]
	v_pk_mul_f32 v[42:43], v[42:43], v[122:123] op_sel_hi:[1,0]
	v_pk_mul_f32 v[40:41], v[40:41], v[122:123] op_sel_hi:[1,0]
	v_pk_mul_f32 v[38:39], v[38:39], v[122:123] op_sel_hi:[1,0]
	v_pk_mul_f32 v[36:37], v[36:37], v[122:123] op_sel_hi:[1,0]
	v_pk_mul_f32 v[34:35], v[34:35], v[122:123] op_sel_hi:[1,0]
	v_pk_mul_f32 v[32:33], v[32:33], v[122:123] op_sel_hi:[1,0]
	v_mul_f32_e32 v120, v120, v122

; #define LAS __attribute__((address_space(3)))
; DI void expsum(f32x16& p, float& l_reg, bf16x8& pa0, bf16x8& pa1) {
; #pragma unroll
;     for (int r = 0; r < 16; ++r) p[r] = __builtin_amdgcn_exp2f(p[r]);
;     float ps = 0.f;
; #pragma unroll
;     for (int r = 0; r < 16; ++r) ps += p[r];
;     l_reg += ps; asm volatile("" : "+v"(l_reg));
;     ...
;     ATT_PK4(p, 0, pa0); ATT_PK4(p, 8, pa1);
;     ...
; }
; DI int v_rd_base(int lane) { return ((lane & 3) << 3) | (((lane >> 2) & 3) << 6) | (((lane >> 4) & 1) << 5) | (((lane >> 5) & 1) << 8); }
; template <int OFF> DI s16x4 tr_read(int vb) { s16x4 r; asm volatile("ds_read_b64_tr_b16 %0, %1 offset:%2" : "=&v"(r) : "v"(vb), "i"(OFF) : "memory"); return r; }
; template <int H> DI void v_reads(s16x4* vf, int vb) {
;     vf[0] = tr_read<v_rd_off(0, 2 * H, 0)>(vb); vf[1] = tr_read<v_rd_off(0, 2 * H, 1)>(vb); vf[2] = tr_read<v_rd_off(0, 2 * H + 1, 0)>(vb); vf[3] = tr_read<v_rd_off(0, 2 * H + 1, 1)>(vb);
;     vf[4] = tr_read<v_rd_off(1, 2 * H, 0)>(vb); vf[5] = tr_read<v_rd_off(1, 2 * H, 1)>(vb); vf[6] = tr_read<v_rd_off(1, 2 * H + 1, 0)>(vb); vf[7] = tr_read<v_rd_off(1, 2 * H + 1, 1)>(vb);
;     vf[8] = tr_read<v_rd_off(2, 2 * H, 0)>(vb); vf[9] = tr_read<v_rd_off(2, 2 * H, 1)>(vb); vf[10] = tr_read<v_rd_off(2, 2 * H + 1, 0)>(vb); vf[11] = tr_read<v_rd_off(2, 2 * H + 1, 1)>(vb);
;     vf[12] = tr_read<v_rd_off(3, 2 * H, 0)>(vb); vf[13] = tr_read<v_rd_off(3, 2 * H, 1)>(vb); vf[14] = tr_read<v_rd_off(3, 2 * H + 1, 0)>(vb); vf[15] = tr_read<v_rd_off(3, 2 * H + 1, 1)>(vb);
; }
; DI void pv_mma(f32x16* o, const s16x4* vf, bf16x8 pa0, bf16x8 pa1) {
;     ...
; #pragma unroll
;     for (int d0 = 0; d0 < 4; ++d0) {
;         o[d0] = __builtin_amdgcn_mfma_f32_32x32x16_bf16(pa0, ATT_PK(vf[4 * d0], vf[4 * d0 + 1]), o[d0], 0, 0, 0);
;         o[d0] = __builtin_amdgcn_mfma_f32_32x32x16_bf16(pa1, ATT_PK(vf[4 * d0 + 2], vf[4 * d0 + 3]), o[d0], 0, 0, 0); }
;     ...
; }
; template <int DQK, int D0A, int D0B> DI void k_reads(bf16x8* kf, const LAS unsigned char* Ks, int half, int r32, int hi) {
; #pragma unroll
;     for (int d0 = D0A; d0 < D0B; ++d0) kf[d0 - D0A] = *(const LAS bf16x8*)(Ks + half * (32 * DQK * 2) + kswz<DQK>(r32, (d0 * 16 + hi * 8) * 2));
; }
; template <int D0A, int D0B> DI void qk_mma(f32x16& p, const bf16x8* kf, const bf16x8* qr) {
; #pragma unroll
;     for (int d0 = D0A; d0 < D0B; ++d0) {
.LBB0_1955:
	s_add_i32 s3, s22, 0xffffc000
	s_and_b32 s3, s3, 0x6000
	v_add_u32_e32 v123, s3, v114
	v_add_u32_e32 v140, v123, v118
	v_add_u32_e32 v136, v123, v117
	v_add_u32_e32 v132, v123, v116
	v_add_u32_e32 v123, v123, v115
	ds_read_b128 v[124:127], v123
	ds_read_b128 v[132:135], v132
	ds_read_b128 v[136:139], v136
	ds_read_b128 v[140:143], v140
	ds_read_b64_tr_b16 v[144:145], v121 offset:0x2000
	ds_read_b64_tr_b16 v[146:147], v121 offset:0x2800
	ds_read_b64_tr_b16 v[148:149], v121 offset:0x3000
	ds_read_b64_tr_b16 v[150:151], v121 offset:0x3800
	ds_read_b64_tr_b16 v[152:153], v121 offset:0x2200
	ds_read_b64_tr_b16 v[154:155], v121 offset:0x2a00
	ds_read_b64_tr_b16 v[156:157], v121 offset:0x3200
	ds_read_b64_tr_b16 v[158:159], v121 offset:0x3a00
	ds_read_b64_tr_b16 v[162:163], v121 offset:0x2400
	ds_read_b64_tr_b16 v[164:165], v121 offset:0x2c00
	ds_read_b64_tr_b16 v[166:167], v121 offset:0x3400
	ds_read_b64_tr_b16 v[168:169], v121 offset:0x3c00
	ds_read_b64_tr_b16 v[170:171], v121 offset:0x2600
	ds_read_b64_tr_b16 v[172:173], v121 offset:0x2e00
	ds_read_b64_tr_b16 v[174:175], v121 offset:0x3600
	ds_read_b64_tr_b16 v[176:177], v121 offset:0x3e00
	s_setprio 1
	v_exp_f32_e32 v64, v64
	v_exp_f32_e32 v65, v65
	v_exp_f32_e32 v66, v66
	v_exp_f32_e32 v67, v67
	v_exp_f32_e32 v68, v68
	v_add_f32_e32 v121, 0, v64
	v_exp_f32_e32 v69, v69
	v_add_f32_e32 v121, v65, v121
	v_exp_f32_e32 v70, v70
	v_add_f32_e32 v121, v66, v121
	v_exp_f32_e32 v71, v71
	v_add_f32_e32 v121, v67, v121
	v_exp_f32_e32 v72, v72
	v_add_f32_e32 v121, v68, v121
	v_exp_f32_e32 v73, v73
	v_add_f32_e32 v121, v69, v121
	v_exp_f32_e32 v74, v74
	v_add_f32_e32 v121, v70, v121
	v_exp_f32_e32 v75, v75
	v_add_f32_e32 v121, v71, v121
	v_exp_f32_e32 v76, v76
	v_add_f32_e32 v121, v72, v121
	v_exp_f32_e32 v77, v77
	v_add_f32_e32 v121, v73, v121
	v_exp_f32_e32 v78, v78
	v_add_f32_e32 v121, v74, v121
	v_exp_f32_e32 v79, v79
	v_add_f32_e32 v121, v75, v121
	v_add_f32_e32 v121, v76, v121
	v_add_f32_e32 v121, v77, v121
	v_add_f32_e32 v121, v78, v121
	v_add_f32_e32 v121, v79, v121
	v_add_f32_e32 v120, v120, v121
	v_cvt_pk_bf16_f32 v64, v64, v65
	v_cvt_pk_bf16_f32 v65, v66, v67
	v_cvt_pk_bf16_f32 v66, v68, v69
	v_cvt_pk_bf16_f32 v67, v70, v71
	v_cvt_pk_bf16_f32 v68, v72, v73
	v_cvt_pk_bf16_f32 v69, v74, v75
	v_cvt_pk_bf16_f32 v70, v76, v77
	v_cvt_pk_bf16_f32 v71, v78, v79
	s_nop 0
	v_permlane32_swap_b32_e32 v64, v66
	v_permlane32_swap_b32_e32 v65, v67
	v_permlane32_swap_b32_e32 v68, v70
	v_permlane32_swap_b32_e32 v69, v71
	s_waitcnt lgkmcnt(0)
	s_setprio 0
	v_mfma_f32_32x32x16_bf16 v[0:15], v[64:67], v[144:147], v[0:15]
	s_cmp_lt_i32 s0, s47
	s_cselect_b64 s[74:75], -1, 0
	s_cmp_ge_i32 s0, s52
	s_cselect_b64 s[90:91], -1, 0
	s_or_b64 s[74:75], s[74:75], s[90:91]
	s_and_b64 vcc, exec, s[74:75]
	v_mfma_f32_32x32x16_bf16 v[48:63], v[64:67], v[152:155], v[48:63]
	v_mfma_f32_32x32x16_bf16 v[16:31], v[64:67], v[162:165], v[16:31]
	v_mfma_f32_32x32x16_bf16 v[32:47], v[64:67], v[170:173], v[32:47]
	v_mfma_f32_32x32x16_bf16 v[0:15], v[68:71], v[148:151], v[0:15]
	v_mfma_f32_32x32x16_bf16 v[48:63], v[68:71], v[156:159], v[48:63]
	v_mfma_f32_32x32x16_bf16 v[16:31], v[68:71], v[166:169], v[16:31]
	v_mfma_f32_32x32x16_bf16 v[32:47], v[68:71], v[174:177], v[32:47]
	s_waitcnt lgkmcnt(0)
	v_mfma_f32_32x32x16_bf16 v[64:79], v[124:127], v[92:95], 0
	v_mfma_f32_32x32x16_bf16 v[64:79], v[132:135], v[88:91], v[64:79]
	v_mfma_f32_32x32x16_bf16 v[64:79], v[136:139], v[84:87], v[64:79]
	v_mfma_f32_32x32x16_bf16 v[64:79], v[140:143], v[80:83], v[64:79]
	s_cbranch_vccnz .LBB0_1957
	v_add_u32_e32 v136, 0x28988, v122
	v_add_u32_e32 v138, 0x289a0, v122
	v_add_u32_e32 v140, 0x289a8, v122
	v_add_u32_e32 v123, 0x289c0, v122
	v_add_u32_e32 v124, 0x289c8, v122
	v_add_u32_e32 v126, 0x289e0, v122
	v_add_u32_e32 v132, 0x289e8, v122
	v_add_u32_e32 v121, 0x28980, v122
	ds_read2_b32 v[122:123], v123 offset1:1
	ds_read2_b32 v[124:125], v124 offset1:1
	ds_read2_b32 v[126:127], v126 offset1:1
	ds_read2_b32 v[132:133], v132 offset1:1
	ds_read2_b32 v[134:135], v121 offset1:1
	ds_read2_b32 v[136:137], v136 offset1:1
	ds_read2_b32 v[138:139], v138 offset1:1
	ds_read2_b32 v[140:141], v140 offset1:1
	s_waitcnt lgkmcnt(0)
	v_pk_add_f32 v[78:79], v[78:79], v[132:133]
	v_pk_add_f32 v[76:77], v[76:77], v[126:127]
	v_pk_add_f32 v[74:75], v[74:75], v[124:125]
	v_pk_add_f32 v[72:73], v[72:73], v[122:123]
	v_pk_add_f32 v[70:71], v[70:71], v[140:141]
	v_pk_add_f32 v[68:69], v[68:69], v[138:139]
	v_pk_add_f32 v[66:67], v[66:67], v[136:137]
	v_pk_add_f32 v[64:65], v[64:65], v[134:135]

; #define SBAR() __builtin_amdgcn_sched_barrier(0)
; #define ATT_DMA_K(t) do { const bf16_t* kg_ = Kh + (size_t)(t) * 64 * LDK; LAS unsigned char* sb_ = lds + ((t) & 3) * KBUF; \
;     _Pragma("unroll") for (int i_ = 0; i_ < NKP; ++i_) __builtin_amdgcn_global_load_lds((const unsigned*)(kg_ + kgo[i_]), (LAS unsigned*)(sb_ + (wid + 8 * i_) * 1024), 16, 0, 0); } while (0)
; #define ATT_DMA_V(t, vs) do { const bf16_t* vg_ = Vh + (size_t)(t) * 64 * LDV; LAS unsigned char* sb_ = lds + V_OFF + (vs) * SHM_V; \
;     _Pragma("unroll") for (int i_ = 0; i_ < 2; ++i_) __builtin_amdgcn_global_load_lds((const unsigned*)(vg_ + vgo[i_]), (LAS unsigned*)(sb_ + (2 * wid + i_) * 1024), 16, 0, 0); } while (0)
; #define ATT_SEG(t) do { if constexpr (MODE != 0) { if (((t) == tL && tL > 0) || (t) == tR) { const float f_ = (t) == tR ? fR : fL; l_reg *= f_; \
;     _Pragma("unroll") for (int d = 0; d < 4; ++d) _Pragma("unroll") for (int r = 0; r < 16; ++r) o[d][r] *= f_; } } } while (0)
; #define ATT_TOP(N) do { asm volatile("s_waitcnt vmcnt(%0)" :: "n"(N) : "memory"); __builtin_amdgcn_s_barrier(); asm volatile("" ::: "memory"); } while (0)
; template <int DQK, int MODE, int LDQ, int LDK, int LDV> ...
;     ...
;     for (int j = 0; j < NT; ++j) {
;         if (j + 2 < NT) ATT_TOP(NKP + 2); else ATT_TOP(0);
;         if (j + 3 < NT) ATT_DMA_K(j + 3);
;         if (j + 2 < NT) ATT_DMA_V(j + 2, v2);
;         ATT_SEG(j); SBAR();
.LBB0_1959:
	s_add_i32 s0, s48, s2
	s_waitcnt vmcnt(3)
	s_barrier
	s_add_i32 s1, s0, 0x400
	v_lshl_add_u64 v[96:97], v[96:97], 1, s[56:57]
	s_mov_b32 m0, s0
	v_lshl_add_u64 v[98:99], v[98:99], 1, s[56:57]
	global_load_lds_dwordx4 v[96:97], off
	s_mov_b32 m0, s1
	s_cmp_lg_u32 s47, 61
	global_load_lds_dwordx4 v[98:99], off
	s_cselect_b64 s[0:1], -1, 0
	s_cmp_eq_u32 s45, 61
	s_cselect_b64 s[2:3], -1, 0
	s_cmp_lg_u32 s45, 61
	s_cselect_b64 s[4:5], -1, 0
	s_and_b64 s[0:1], s[4:5], s[0:1]
	s_and_b64 vcc, exec, s[0:1]
	s_cbranch_vccnz .LBB0_1961
	v_cndmask_b32_e64 v96, v112, v113, s[2:3]
	v_pk_mul_f32 v[14:15], v[14:15], v[96:97] op_sel_hi:[1,0]
	v_pk_mul_f32 v[12:13], v[12:13], v[96:97] op_sel_hi:[1,0]
	v_pk_mul_f32 v[10:11], v[10:11], v[96:97] op_sel_hi:[1,0]
	v_pk_mul_f32 v[8:9], v[8:9], v[96:97] op_sel_hi:[1,0]
	v_pk_mul_f32 v[6:7], v[6:7], v[96:97] op_sel_hi:[1,0]
	v_pk_mul_f32 v[4:5], v[4:5], v[96:97] op_sel_hi:[1,0]
	v_pk_mul_f32 v[2:3], v[2:3], v[96:97] op_sel_hi:[1,0]
	v_pk_mul_f32 v[0:1], v[0:1], v[96:97] op_sel_hi:[1,0]
	v_pk_mul_f32 v[62:63], v[62:63], v[96:97] op_sel_hi:[1,0]
	v_pk_mul_f32 v[60:61], v[60:61], v[96:97] op_sel_hi:[1,0]
	v_pk_mul_f32 v[58:59], v[58:59], v[96:97] op_sel_hi:[1,0]
	v_pk_mul_f32 v[56:57], v[56:57], v[96:97] op_sel_hi:[1,0]
	v_pk_mul_f32 v[54:55], v[54:55], v[96:97] op_sel_hi:[1,0]
	v_pk_mul_f32 v[52:53], v[52:53], v[96:97] op_sel_hi:[1,0]
	v_pk_mul_f32 v[50:51], v[50:51], v[96:97] op_sel_hi:[1,0]
	v_pk_mul_f32 v[48:49], v[48:49], v[96:97] op_sel_hi:[1,0]
	v_pk_mul_f32 v[30:31], v[30:31], v[96:97] op_sel_hi:[1,0]
	v_pk_mul_f32 v[28:29], v[28:29], v[96:97] op_sel_hi:[1,0]
	v_pk_mul_f32 v[26:27], v[26:27], v[96:97] op_sel_hi:[1,0]
	v_pk_mul_f32 v[24:25], v[24:25], v[96:97] op_sel_hi:[1,0]
	v_pk_mul_f32 v[22:23], v[22:23], v[96:97] op_sel_hi:[1,0]
	v_pk_mul_f32 v[20:21], v[20:21], v[96:97] op_sel_hi:[1,0]
	v_pk_mul_f32 v[18:19], v[18:19], v[96:97] op_sel_hi:[1,0]
	v_pk_mul_f32 v[16:17], v[16:17], v[96:97] op_sel_hi:[1,0]
	v_pk_mul_f32 v[46:47], v[46:47], v[96:97] op_sel_hi:[1,0]
	v_pk_mul_f32 v[44:45], v[44:45], v[96:97] op_sel_hi:[1,0]
	v_pk_mul_f32 v[42:43], v[42:43], v[96:97] op_sel_hi:[1,0]
	v_pk_mul_f32 v[40:41], v[40:41], v[96:97] op_sel_hi:[1,0]
	v_pk_mul_f32 v[38:39], v[38:39], v[96:97] op_sel_hi:[1,0]
	v_pk_mul_f32 v[36:37], v[36:37], v[96:97] op_sel_hi:[1,0]
	v_pk_mul_f32 v[34:35], v[34:35], v[96:97] op_sel_hi:[1,0]
	v_pk_mul_f32 v[32:33], v[32:33], v[96:97] op_sel_hi:[1,0]
	v_mul_f32_e32 v120, v120, v96

; #define LAS __attribute__((address_space(3)))
; DI void expsum(f32x16& p, float& l_reg, bf16x8& pa0, bf16x8& pa1) {
; #pragma unroll
;     for (int r = 0; r < 16; ++r) p[r] = __builtin_amdgcn_exp2f(p[r]);
;     float ps = 0.f;
; #pragma unroll
;     for (int r = 0; r < 16; ++r) ps += p[r];
;     l_reg += ps; asm volatile("" : "+v"(l_reg));
;     ...
;     ATT_PK4(p, 0, pa0); ATT_PK4(p, 8, pa1);
;     ...
; }
; DI int v_rd_base(int lane) { return ((lane & 3) << 3) | (((lane >> 2) & 3) << 6) | (((lane >> 4) & 1) << 5) | (((lane >> 5) & 1) << 8); }
; template <int OFF> DI s16x4 tr_read(int vb) { s16x4 r; asm volatile("ds_read_b64_tr_b16 %0, %1 offset:%2" : "=&v"(r) : "v"(vb), "i"(OFF) : "memory"); return r; }
; template <int H> DI void v_reads(s16x4* vf, int vb) {
;     vf[0] = tr_read<v_rd_off(0, 2 * H, 0)>(vb); vf[1] = tr_read<v_rd_off(0, 2 * H, 1)>(vb); vf[2] = tr_read<v_rd_off(0, 2 * H + 1, 0)>(vb); vf[3] = tr_read<v_rd_off(0, 2 * H + 1, 1)>(vb);
;     vf[4] = tr_read<v_rd_off(1, 2 * H, 0)>(vb); vf[5] = tr_read<v_rd_off(1, 2 * H, 1)>(vb); vf[6] = tr_read<v_rd_off(1, 2 * H + 1, 0)>(vb); vf[7] = tr_read<v_rd_off(1, 2 * H + 1, 1)>(vb);
;     vf[8] = tr_read<v_rd_off(2, 2 * H, 0)>(vb); vf[9] = tr_read<v_rd_off(2, 2 * H, 1)>(vb); vf[10] = tr_read<v_rd_off(2, 2 * H + 1, 0)>(vb); vf[11] = tr_read<v_rd_off(2, 2 * H + 1, 1)>(vb);
;     vf[12] = tr_read<v_rd_off(3, 2 * H, 0)>(vb); vf[13] = tr_read<v_rd_off(3, 2 * H, 1)>(vb); vf[14] = tr_read<v_rd_off(3, 2 * H + 1, 0)>(vb); vf[15] = tr_read<v_rd_off(3, 2 * H + 1, 1)>(vb);
; }
; DI void pv_mma(f32x16* o, const s16x4* vf, bf16x8 pa0, bf16x8 pa1) {
;     ...
; #pragma unroll
;     for (int d0 = 0; d0 < 4; ++d0) {
;         o[d0] = __builtin_amdgcn_mfma_f32_32x32x16_bf16(pa0, ATT_PK(vf[4 * d0], vf[4 * d0 + 1]), o[d0], 0, 0, 0);
;         o[d0] = __builtin_amdgcn_mfma_f32_32x32x16_bf16(pa1, ATT_PK(vf[4 * d0 + 2], vf[4 * d0 + 3]), o[d0], 0, 0, 0); }
;     ...
; }
; template <int DQK, int D0A, int D0B> DI void k_reads(bf16x8* kf, const LAS unsigned char* Ks, int half, int r32, int hi) {
; #pragma unroll
;     for (int d0 = D0A; d0 < D0B; ++d0) kf[d0 - D0A] = *(const LAS bf16x8*)(Ks + half * (32 * DQK * 2) + kswz<DQK>(r32, (d0 * 16 + hi * 8) * 2));
; }
; template <int D0A, int D0B> DI void qk_mma(f32x16& p, const bf16x8* kf, const bf16x8* qr) {
; #pragma unroll
;     for (int d0 = D0A; d0 < D0B; ++d0) {
.LBB0_1963:
	ds_read_b128 v[98:101], v107 offset:16384
	ds_read_b128 v[102:105], v108 offset:16384
	ds_read_b128 v[114:117], v109 offset:16384
	ds_read_b128 v[118:121], v110 offset:16384
	ds_read_b64_tr_b16 v[122:123], v96 offset:0x2000
	ds_read_b64_tr_b16 v[124:125], v96 offset:0x2800
	ds_read_b64_tr_b16 v[132:133], v96 offset:0x3000
	ds_read_b64_tr_b16 v[134:135], v96 offset:0x3800
	ds_read_b64_tr_b16 v[136:137], v96 offset:0x2200
	ds_read_b64_tr_b16 v[138:139], v96 offset:0x2a00
	ds_read_b64_tr_b16 v[140:141], v96 offset:0x3200
	ds_read_b64_tr_b16 v[142:143], v96 offset:0x3a00
	ds_read_b64_tr_b16 v[144:145], v96 offset:0x2400
	ds_read_b64_tr_b16 v[146:147], v96 offset:0x2c00
	ds_read_b64_tr_b16 v[148:149], v96 offset:0x3400
	ds_read_b64_tr_b16 v[150:151], v96 offset:0x3c00
	ds_read_b64_tr_b16 v[152:153], v96 offset:0x2600
	ds_read_b64_tr_b16 v[154:155], v96 offset:0x2e00
	ds_read_b64_tr_b16 v[156:157], v96 offset:0x3600
	ds_read_b64_tr_b16 v[158:159], v96 offset:0x3e00
	s_nop 6
	s_setprio 1
	v_exp_f32_e32 v64, v64
	v_exp_f32_e32 v65, v65
	v_exp_f32_e32 v66, v66
	v_exp_f32_e32 v67, v67
	v_exp_f32_e32 v68, v68
	v_add_f32_e32 v96, 0, v64
	v_exp_f32_e32 v69, v69
	v_add_f32_e32 v96, v65, v96
	v_exp_f32_e32 v70, v70
	v_add_f32_e32 v96, v66, v96
	v_exp_f32_e32 v71, v71
	v_add_f32_e32 v96, v67, v96
	v_exp_f32_e32 v72, v72
	v_add_f32_e32 v96, v68, v96
	v_exp_f32_e32 v73, v73
	v_add_f32_e32 v96, v69, v96
	v_exp_f32_e32 v74, v74
	v_add_f32_e32 v96, v70, v96
	v_exp_f32_e32 v75, v75
	v_add_f32_e32 v96, v71, v96
	v_exp_f32_e32 v76, v76
	v_add_f32_e32 v96, v72, v96
	v_exp_f32_e32 v77, v77
	v_add_f32_e32 v96, v73, v96
	v_exp_f32_e32 v78, v78
	v_add_f32_e32 v96, v74, v96
	v_exp_f32_e32 v79, v79
	v_add_f32_e32 v96, v75, v96
	v_add_f32_e32 v96, v76, v96
	v_add_f32_e32 v96, v77, v96
	v_add_f32_e32 v96, v78, v96
	v_add_f32_e32 v96, v79, v96
	v_add_f32_e32 v96, v97, v96
	v_cvt_pk_bf16_f32 v64, v64, v65
	v_cvt_pk_bf16_f32 v65, v66, v67
	v_cvt_pk_bf16_f32 v66, v68, v69
	v_cvt_pk_bf16_f32 v67, v70, v71
	v_cvt_pk_bf16_f32 v68, v72, v73
	v_cvt_pk_bf16_f32 v69, v74, v75
	v_cvt_pk_bf16_f32 v70, v76, v77
	v_cvt_pk_bf16_f32 v71, v78, v79
	s_nop 0
	v_permlane32_swap_b32_e32 v64, v66
	v_permlane32_swap_b32_e32 v65, v67
	v_permlane32_swap_b32_e32 v68, v70
	v_permlane32_swap_b32_e32 v69, v71
	s_waitcnt lgkmcnt(0)
	s_setprio 0
	v_mfma_f32_32x32x16_bf16 v[0:15], v[64:67], v[122:125], v[0:15]
	s_cmp_lt_i32 s47, 63
	s_cselect_b64 s[0:1], -1, 0
	s_cmp_gt_i32 s45, 62
	s_cselect_b64 s[2:3], -1, 0
	s_and_b64 s[0:1], s[0:1], s[2:3]
	v_cndmask_b32_e64 v97, 0, 1, s[0:1]
	v_cmp_ne_u32_e64 s[2:3], 1, v97
	v_mfma_f32_32x32x16_bf16 v[48:63], v[64:67], v[136:139], v[48:63]
	v_sub_u32_e32 v97, 0xf80, v111
	s_andn2_b64 vcc, exec, s[0:1]
	v_lshlrev_b32_e32 v97, 2, v97
	v_mfma_f32_32x32x16_bf16 v[16:31], v[64:67], v[144:147], v[16:31]
	v_mfma_f32_32x32x16_bf16 v[32:47], v[64:67], v[152:155], v[32:47]
	v_mfma_f32_32x32x16_bf16 v[0:15], v[68:71], v[132:135], v[0:15]
	v_mfma_f32_32x32x16_bf16 v[48:63], v[68:71], v[140:143], v[48:63]
	v_mfma_f32_32x32x16_bf16 v[16:31], v[68:71], v[148:151], v[16:31]
	v_mfma_f32_32x32x16_bf16 v[32:47], v[68:71], v[156:159], v[32:47]
	s_waitcnt lgkmcnt(0)
	v_mfma_f32_32x32x16_bf16 v[64:79], v[98:101], v[92:95], 0
	v_mfma_f32_32x32x16_bf16 v[64:79], v[102:105], v[88:91], v[64:79]
	v_mfma_f32_32x32x16_bf16 v[64:79], v[114:117], v[84:87], v[64:79]
	v_mfma_f32_32x32x16_bf16 v[64:79], v[118:121], v[80:83], v[64:79]
	s_cbranch_vccnz .LBB0_1965
	v_add3_u32 v120, s88, v97, v130
	ds_read2_b32 v[98:99], v120 offset0:240 offset1:241
	ds_read2_b32 v[100:101], v120 offset0:242 offset1:243
	ds_read2_b32 v[102:103], v120 offset0:248 offset1:249
	ds_read2_b32 v[104:105], v120 offset0:250 offset1:251
	ds_read2_b32 v[114:115], v120 offset0:224 offset1:225
	ds_read2_b32 v[116:117], v120 offset0:226 offset1:227
	ds_read2_b32 v[118:119], v120 offset0:232 offset1:233
	ds_read2_b32 v[120:121], v120 offset0:234 offset1:235
	s_waitcnt lgkmcnt(0)
	s_nop 0
	v_pk_add_f32 v[78:79], v[78:79], v[104:105]
	v_pk_add_f32 v[76:77], v[76:77], v[102:103]
	v_pk_add_f32 v[74:75], v[74:75], v[100:101]
	v_pk_add_f32 v[72:73], v[72:73], v[98:99]
	v_pk_add_f32 v[70:71], v[70:71], v[120:121]
	v_pk_add_f32 v[68:69], v[68:69], v[118:119]
	v_pk_add_f32 v[66:67], v[66:67], v[116:117]
	v_pk_add_f32 v[64:65], v[64:65], v[114:115]
.LBB0_1965:
	s_cmp_lg_u32 s47, 62
	s_cselect_b64 s[0:1], -1, 0
	s_cmp_eq_u32 s45, 62
	s_cselect_b64 s[4:5], -1, 0
	s_cmp_lg_u32 s45, 62
	s_waitcnt vmcnt(0)
	s_barrier
	s_cselect_b64 s[6:7], -1, 0
	s_and_b64 s[0:1], s[6:7], s[0:1]
	s_and_b64 vcc, exec, s[0:1]
	s_cbranch_vccnz .LBB0_1967
	v_cndmask_b32_e64 v98, v112, v113, s[4:5]
	v_pk_mul_f32 v[14:15], v[98:99], v[14:15] op_sel_hi:[0,1]
	v_pk_mul_f32 v[12:13], v[98:99], v[12:13] op_sel_hi:[0,1]
	v_pk_mul_f32 v[10:11], v[98:99], v[10:11] op_sel_hi:[0,1]
	v_pk_mul_f32 v[8:9], v[98:99], v[8:9] op_sel_hi:[0,1]
	v_pk_mul_f32 v[6:7], v[98:99], v[6:7] op_sel_hi:[0,1]
	v_pk_mul_f32 v[4:5], v[98:99], v[4:5] op_sel_hi:[0,1]
	v_pk_mul_f32 v[2:3], v[98:99], v[2:3] op_sel_hi:[0,1]
	v_pk_mul_f32 v[0:1], v[98:99], v[0:1] op_sel_hi:[0,1]
	v_pk_mul_f32 v[62:63], v[98:99], v[62:63] op_sel_hi:[0,1]
	v_pk_mul_f32 v[60:61], v[98:99], v[60:61] op_sel_hi:[0,1]
	v_pk_mul_f32 v[58:59], v[98:99], v[58:59] op_sel_hi:[0,1]
	v_pk_mul_f32 v[56:57], v[98:99], v[56:57] op_sel_hi:[0,1]
	v_pk_mul_f32 v[54:55], v[98:99], v[54:55] op_sel_hi:[0,1]
	v_pk_mul_f32 v[52:53], v[98:99], v[52:53] op_sel_hi:[0,1]
	v_pk_mul_f32 v[50:51], v[98:99], v[50:51] op_sel_hi:[0,1]
	v_pk_mul_f32 v[48:49], v[98:99], v[48:49] op_sel_hi:[0,1]
	v_pk_mul_f32 v[30:31], v[98:99], v[30:31] op_sel_hi:[0,1]
	v_pk_mul_f32 v[28:29], v[98:99], v[28:29] op_sel_hi:[0,1]
	v_pk_mul_f32 v[26:27], v[98:99], v[26:27] op_sel_hi:[0,1]
	v_pk_mul_f32 v[24:25], v[98:99], v[24:25] op_sel_hi:[0,1]
	v_pk_mul_f32 v[22:23], v[98:99], v[22:23] op_sel_hi:[0,1]
	v_pk_mul_f32 v[20:21], v[98:99], v[20:21] op_sel_hi:[0,1]
	v_pk_mul_f32 v[18:19], v[98:99], v[18:19] op_sel_hi:[0,1]
	v_pk_mul_f32 v[16:17], v[98:99], v[16:17] op_sel_hi:[0,1]
	v_pk_mul_f32 v[46:47], v[98:99], v[46:47] op_sel_hi:[0,1]
	v_pk_mul_f32 v[44:45], v[98:99], v[44:45] op_sel_hi:[0,1]
	v_pk_mul_f32 v[42:43], v[98:99], v[42:43] op_sel_hi:[0,1]
	v_pk_mul_f32 v[40:41], v[98:99], v[40:41] op_sel_hi:[0,1]
	v_pk_mul_f32 v[38:39], v[98:99], v[38:39] op_sel_hi:[0,1]
	v_pk_mul_f32 v[36:37], v[98:99], v[36:37] op_sel_hi:[0,1]
	v_pk_mul_f32 v[34:35], v[98:99], v[34:35] op_sel_hi:[0,1]
	v_pk_mul_f32 v[32:33], v[98:99], v[32:33] op_sel_hi:[0,1]
	v_mul_f32_e32 v96, v98, v96

; #define LAS __attribute__((address_space(3)))
; DI void expsum(f32x16& p, float& l_reg, bf16x8& pa0, bf16x8& pa1) {
; #pragma unroll
;     for (int r = 0; r < 16; ++r) p[r] = __builtin_amdgcn_exp2f(p[r]);
;     float ps = 0.f;
; #pragma unroll
;     for (int r = 0; r < 16; ++r) ps += p[r];
;     l_reg += ps; asm volatile("" : "+v"(l_reg));
;     ...
;     ATT_PK4(p, 0, pa0); ATT_PK4(p, 8, pa1);
;     ...
; }
; DI int v_rd_base(int lane) { return ((lane & 3) << 3) | (((lane >> 2) & 3) << 6) | (((lane >> 4) & 1) << 5) | (((lane >> 5) & 1) << 8); }
; template <int OFF> DI s16x4 tr_read(int vb) { s16x4 r; asm volatile("ds_read_b64_tr_b16 %0, %1 offset:%2" : "=&v"(r) : "v"(vb), "i"(OFF) : "memory"); return r; }
; template <int H> DI void v_reads(s16x4* vf, int vb) {
;     vf[0] = tr_read<v_rd_off(0, 2 * H, 0)>(vb); vf[1] = tr_read<v_rd_off(0, 2 * H, 1)>(vb); vf[2] = tr_read<v_rd_off(0, 2 * H + 1, 0)>(vb); vf[3] = tr_read<v_rd_off(0, 2 * H + 1, 1)>(vb);
;     vf[4] = tr_read<v_rd_off(1, 2 * H, 0)>(vb); vf[5] = tr_read<v_rd_off(1, 2 * H, 1)>(vb); vf[6] = tr_read<v_rd_off(1, 2 * H + 1, 0)>(vb); vf[7] = tr_read<v_rd_off(1, 2 * H + 1, 1)>(vb);
;     vf[8] = tr_read<v_rd_off(2, 2 * H, 0)>(vb); vf[9] = tr_read<v_rd_off(2, 2 * H, 1)>(vb); vf[10] = tr_read<v_rd_off(2, 2 * H + 1, 0)>(vb); vf[11] = tr_read<v_rd_off(2, 2 * H + 1, 1)>(vb);
;     vf[12] = tr_read<v_rd_off(3, 2 * H, 0)>(vb); vf[13] = tr_read<v_rd_off(3, 2 * H, 1)>(vb); vf[14] = tr_read<v_rd_off(3, 2 * H + 1, 0)>(vb); vf[15] = tr_read<v_rd_off(3, 2 * H + 1, 1)>(vb);
; }
; DI void pv_mma(f32x16* o, const s16x4* vf, bf16x8 pa0, bf16x8 pa1) {
;     ...
; #pragma unroll
;     for (int d0 = 0; d0 < 4; ++d0) {
;         o[d0] = __builtin_amdgcn_mfma_f32_32x32x16_bf16(pa0, ATT_PK(vf[4 * d0], vf[4 * d0 + 1]), o[d0], 0, 0, 0);
;         o[d0] = __builtin_amdgcn_mfma_f32_32x32x16_bf16(pa1, ATT_PK(vf[4 * d0 + 2], vf[4 * d0 + 3]), o[d0], 0, 0, 0); }
;     ...
; }
; template <int DQK, int D0A, int D0B> DI void k_reads(bf16x8* kf, const LAS unsigned char* Ks, int half, int r32, int hi) {
; #pragma unroll
;     for (int d0 = D0A; d0 < D0B; ++d0) kf[d0 - D0A] = *(const LAS bf16x8*)(Ks + half * (32 * DQK * 2) + kswz<DQK>(r32, (d0 * 16 + hi * 8) * 2));
; }
; template <int D0A, int D0B> DI void qk_mma(f32x16& p, const bf16x8* kf, const bf16x8* qr) {
; #pragma unroll
;     for (int d0 = D0A; d0 < D0B; ++d0) {
.LBB0_1969:
	ds_read_b128 v[100:103], v107 offset:24576
	ds_read_b128 v[114:117], v108 offset:24576
	ds_read_b128 v[118:121], v109 offset:24576
	ds_read_b128 v[122:125], v110 offset:24576
	ds_read_b64_tr_b16 v[132:133], v98 offset:0x2000
	ds_read_b64_tr_b16 v[134:135], v98 offset:0x2800
	ds_read_b64_tr_b16 v[136:137], v98 offset:0x3000
	ds_read_b64_tr_b16 v[138:139], v98 offset:0x3800
	ds_read_b64_tr_b16 v[140:141], v98 offset:0x2200
	ds_read_b64_tr_b16 v[142:143], v98 offset:0x2a00
	ds_read_b64_tr_b16 v[144:145], v98 offset:0x3200
	ds_read_b64_tr_b16 v[146:147], v98 offset:0x3a00
	ds_read_b64_tr_b16 v[148:149], v98 offset:0x2400
	ds_read_b64_tr_b16 v[150:151], v98 offset:0x2c00
	ds_read_b64_tr_b16 v[152:153], v98 offset:0x3400
	ds_read_b64_tr_b16 v[154:155], v98 offset:0x3c00
	ds_read_b64_tr_b16 v[156:157], v98 offset:0x2600
	ds_read_b64_tr_b16 v[158:159], v98 offset:0x2e00
	ds_read_b64_tr_b16 v[162:163], v98 offset:0x3600
	ds_read_b64_tr_b16 v[164:165], v98 offset:0x3e00
	s_nop 6
	s_setprio 1
	v_exp_f32_e32 v64, v64
	v_exp_f32_e32 v65, v65
	v_exp_f32_e32 v66, v66
	v_exp_f32_e32 v67, v67
	v_exp_f32_e32 v68, v68
	v_add_f32_e32 v97, 0, v64
	v_exp_f32_e32 v69, v69
	v_add_f32_e32 v97, v65, v97
	v_exp_f32_e32 v70, v70
	v_add_f32_e32 v97, v66, v97
	v_exp_f32_e32 v71, v71
	v_add_f32_e32 v97, v67, v97
	v_exp_f32_e32 v72, v72
	v_add_f32_e32 v97, v68, v97
	v_exp_f32_e32 v73, v73
	v_add_f32_e32 v97, v69, v97
	v_exp_f32_e32 v74, v74
	v_add_f32_e32 v97, v70, v97
	v_exp_f32_e32 v75, v75
	v_add_f32_e32 v97, v71, v97
	v_exp_f32_e32 v76, v76
	v_add_f32_e32 v97, v72, v97
	v_exp_f32_e32 v77, v77
	v_add_f32_e32 v97, v73, v97
	v_exp_f32_e32 v78, v78
	v_add_f32_e32 v97, v74, v97
	v_exp_f32_e32 v79, v79
	v_add_f32_e32 v97, v75, v97
	v_add_f32_e32 v97, v76, v97
	v_add_f32_e32 v97, v77, v97
	v_add_f32_e32 v97, v78, v97
	v_add_f32_e32 v97, v79, v97
	v_add_f32_e32 v96, v96, v97
	v_cvt_pk_bf16_f32 v64, v64, v65
	v_cvt_pk_bf16_f32 v65, v66, v67
	v_cvt_pk_bf16_f32 v66, v68, v69
	v_cvt_pk_bf16_f32 v67, v70, v71
	v_cvt_pk_bf16_f32 v68, v72, v73
	v_cvt_pk_bf16_f32 v69, v74, v75
	v_cvt_pk_bf16_f32 v70, v76, v77
	v_cvt_pk_bf16_f32 v71, v78, v79
	s_nop 0
	v_permlane32_swap_b32_e32 v64, v66
	v_permlane32_swap_b32_e32 v65, v67
	v_permlane32_swap_b32_e32 v68, v70
	v_permlane32_swap_b32_e32 v69, v71
	s_waitcnt lgkmcnt(0)
	s_setprio 0
	v_mfma_f32_32x32x16_bf16 v[0:15], v[64:67], v[132:135], v[0:15]
	s_cmp_lt_i32 s47, 64
	s_cselect_b64 s[0:1], -1, 0
	s_cmp_gt_i32 s45, 63
	s_cselect_b64 s[2:3], -1, 0
	s_and_b64 s[0:1], s[2:3], s[0:1]
	v_cndmask_b32_e64 v97, 0, 1, s[0:1]
	v_cmp_ne_u32_e64 s[2:3], 1, v97
	v_mfma_f32_32x32x16_bf16 v[48:63], v[64:67], v[140:143], v[48:63]
	v_sub_u32_e32 v97, 0xfc0, v111
	s_andn2_b64 vcc, exec, s[0:1]
	v_lshlrev_b32_e32 v97, 2, v97
	v_mfma_f32_32x32x16_bf16 v[16:31], v[64:67], v[148:151], v[16:31]
	v_mfma_f32_32x32x16_bf16 v[32:47], v[64:67], v[156:159], v[32:47]
	v_mfma_f32_32x32x16_bf16 v[0:15], v[68:71], v[136:139], v[0:15]
	v_mfma_f32_32x32x16_bf16 v[48:63], v[68:71], v[144:147], v[48:63]
	v_mfma_f32_32x32x16_bf16 v[16:31], v[68:71], v[152:155], v[16:31]
	v_mfma_f32_32x32x16_bf16 v[32:47], v[68:71], v[162:165], v[32:47]
	s_waitcnt lgkmcnt(0)
	v_mfma_f32_32x32x16_bf16 v[64:79], v[100:103], v[92:95], 0
	v_mfma_f32_32x32x16_bf16 v[64:79], v[114:117], v[88:91], v[64:79]
	v_mfma_f32_32x32x16_bf16 v[64:79], v[118:121], v[84:87], v[64:79]
	v_mfma_f32_32x32x16_bf16 v[64:79], v[122:125], v[80:83], v[64:79]
	s_cbranch_vccnz .LBB0_1971
	v_add3_u32 v111, s88, v97, v130
	ds_read2_b32 v[98:99], v111 offset0:240 offset1:241
	ds_read2_b32 v[100:101], v111 offset0:242 offset1:243
	ds_read2_b32 v[102:103], v111 offset0:248 offset1:249
	ds_read2_b32 v[104:105], v111 offset0:250 offset1:251
	ds_read2_b32 v[114:115], v111 offset0:224 offset1:225
	ds_read2_b32 v[116:117], v111 offset0:226 offset1:227
	ds_read2_b32 v[118:119], v111 offset0:232 offset1:233
	ds_read2_b32 v[120:121], v111 offset0:234 offset1:235
	s_waitcnt lgkmcnt(0)
	s_nop 0
	v_pk_add_f32 v[78:79], v[78:79], v[104:105]
	v_pk_add_f32 v[76:77], v[76:77], v[102:103]
	v_pk_add_f32 v[74:75], v[74:75], v[100:101]
	v_pk_add_f32 v[72:73], v[72:73], v[98:99]
	v_pk_add_f32 v[70:71], v[70:71], v[120:121]
	v_pk_add_f32 v[68:69], v[68:69], v[118:119]
	v_pk_add_f32 v[66:67], v[66:67], v[116:117]
	v_pk_add_f32 v[64:65], v[64:65], v[114:115]
.LBB0_1971:
	s_cmp_lg_u32 s47, 63
	s_cselect_b64 s[0:1], -1, 0
	s_cmp_eq_u32 s45, 63
	s_cselect_b64 s[4:5], -1, 0
	s_cmp_lg_u32 s45, 63
	s_waitcnt vmcnt(0)
	s_barrier
	s_cselect_b64 s[6:7], -1, 0
	s_and_b64 s[0:1], s[6:7], s[0:1]
	s_and_b64 vcc, exec, s[0:1]
	s_cbranch_vccnz .LBB0_1973
	v_cndmask_b32_e64 v98, v112, v113, s[4:5]
	v_pk_mul_f32 v[14:15], v[98:99], v[14:15] op_sel_hi:[0,1]
	v_pk_mul_f32 v[12:13], v[98:99], v[12:13] op_sel_hi:[0,1]
	v_pk_mul_f32 v[10:11], v[98:99], v[10:11] op_sel_hi:[0,1]
	v_pk_mul_f32 v[8:9], v[98:99], v[8:9] op_sel_hi:[0,1]
	v_pk_mul_f32 v[6:7], v[98:99], v[6:7] op_sel_hi:[0,1]
	v_pk_mul_f32 v[4:5], v[98:99], v[4:5] op_sel_hi:[0,1]
	v_pk_mul_f32 v[2:3], v[98:99], v[2:3] op_sel_hi:[0,1]
	v_pk_mul_f32 v[0:1], v[98:99], v[0:1] op_sel_hi:[0,1]
	v_pk_mul_f32 v[62:63], v[98:99], v[62:63] op_sel_hi:[0,1]
	v_pk_mul_f32 v[60:61], v[98:99], v[60:61] op_sel_hi:[0,1]
	v_pk_mul_f32 v[58:59], v[98:99], v[58:59] op_sel_hi:[0,1]
	v_pk_mul_f32 v[56:57], v[98:99], v[56:57] op_sel_hi:[0,1]
	v_pk_mul_f32 v[54:55], v[98:99], v[54:55] op_sel_hi:[0,1]
	v_pk_mul_f32 v[52:53], v[98:99], v[52:53] op_sel_hi:[0,1]
	v_pk_mul_f32 v[50:51], v[98:99], v[50:51] op_sel_hi:[0,1]
	v_pk_mul_f32 v[48:49], v[98:99], v[48:49] op_sel_hi:[0,1]
	v_pk_mul_f32 v[30:31], v[98:99], v[30:31] op_sel_hi:[0,1]
	v_pk_mul_f32 v[28:29], v[98:99], v[28:29] op_sel_hi:[0,1]
	v_pk_mul_f32 v[26:27], v[98:99], v[26:27] op_sel_hi:[0,1]
	v_pk_mul_f32 v[24:25], v[98:99], v[24:25] op_sel_hi:[0,1]
	v_pk_mul_f32 v[22:23], v[98:99], v[22:23] op_sel_hi:[0,1]
	v_pk_mul_f32 v[20:21], v[98:99], v[20:21] op_sel_hi:[0,1]
	v_pk_mul_f32 v[18:19], v[98:99], v[18:19] op_sel_hi:[0,1]
	v_pk_mul_f32 v[16:17], v[98:99], v[16:17] op_sel_hi:[0,1]
	v_pk_mul_f32 v[46:47], v[98:99], v[46:47] op_sel_hi:[0,1]
	v_pk_mul_f32 v[44:45], v[98:99], v[44:45] op_sel_hi:[0,1]
	v_pk_mul_f32 v[42:43], v[98:99], v[42:43] op_sel_hi:[0,1]
	v_pk_mul_f32 v[40:41], v[98:99], v[40:41] op_sel_hi:[0,1]
	v_pk_mul_f32 v[38:39], v[98:99], v[38:39] op_sel_hi:[0,1]
	v_pk_mul_f32 v[36:37], v[98:99], v[36:37] op_sel_hi:[0,1]
	v_pk_mul_f32 v[34:35], v[98:99], v[34:35] op_sel_hi:[0,1]
	v_pk_mul_f32 v[32:33], v[98:99], v[32:33] op_sel_hi:[0,1]
	v_mul_f32_e32 v96, v98, v96

; #define LAS __attribute__((address_space(3)))
; DI void expsum(f32x16& p, float& l_reg, bf16x8& pa0, bf16x8& pa1) {
; #pragma unroll
;     for (int r = 0; r < 16; ++r) p[r] = __builtin_amdgcn_exp2f(p[r]);
;     float ps = 0.f;
; #pragma unroll
;     for (int r = 0; r < 16; ++r) ps += p[r];
;     l_reg += ps; asm volatile("" : "+v"(l_reg));
;     ...
;     ATT_PK4(p, 0, pa0); ATT_PK4(p, 8, pa1);
;     ...
; }
; DI int v_rd_base(int lane) { return ((lane & 3) << 3) | (((lane >> 2) & 3) << 6) | (((lane >> 4) & 1) << 5) | (((lane >> 5) & 1) << 8); }
; template <int OFF> DI s16x4 tr_read(int vb) { s16x4 r; asm volatile("ds_read_b64_tr_b16 %0, %1 offset:%2" : "=&v"(r) : "v"(vb), "i"(OFF) : "memory"); return r; }
; template <int H> DI void v_reads(s16x4* vf, int vb) {
;     vf[0] = tr_read<v_rd_off(0, 2 * H, 0)>(vb); vf[1] = tr_read<v_rd_off(0, 2 * H, 1)>(vb); vf[2] = tr_read<v_rd_off(0, 2 * H + 1, 0)>(vb); vf[3] = tr_read<v_rd_off(0, 2 * H + 1, 1)>(vb);
;     vf[4] = tr_read<v_rd_off(1, 2 * H, 0)>(vb); vf[5] = tr_read<v_rd_off(1, 2 * H, 1)>(vb); vf[6] = tr_read<v_rd_off(1, 2 * H + 1, 0)>(vb); vf[7] = tr_read<v_rd_off(1, 2 * H + 1, 1)>(vb);
;     vf[8] = tr_read<v_rd_off(2, 2 * H, 0)>(vb); vf[9] = tr_read<v_rd_off(2, 2 * H, 1)>(vb); vf[10] = tr_read<v_rd_off(2, 2 * H + 1, 0)>(vb); vf[11] = tr_read<v_rd_off(2, 2 * H + 1, 1)>(vb);
;     vf[12] = tr_read<v_rd_off(3, 2 * H, 0)>(vb); vf[13] = tr_read<v_rd_off(3, 2 * H, 1)>(vb); vf[14] = tr_read<v_rd_off(3, 2 * H + 1, 0)>(vb); vf[15] = tr_read<v_rd_off(3, 2 * H + 1, 1)>(vb);
; }
; DI void pv_mma(f32x16* o, const s16x4* vf, bf16x8 pa0, bf16x8 pa1) {
;     ...
; #pragma unroll
;     for (int d0 = 0; d0 < 4; ++d0) {
;         o[d0] = __builtin_amdgcn_mfma_f32_32x32x16_bf16(pa0, ATT_PK(vf[4 * d0], vf[4 * d0 + 1]), o[d0], 0, 0, 0);
;         o[d0] = __builtin_amdgcn_mfma_f32_32x32x16_bf16(pa1, ATT_PK(vf[4 * d0 + 2], vf[4 * d0 + 3]), o[d0], 0, 0, 0); }
;     ...
; }
; template <int DQK, int D0A, int D0B> DI void k_reads(bf16x8* kf, const LAS unsigned char* Ks, int half, int r32, int hi) {
; #pragma unroll
;     for (int d0 = D0A; d0 < D0B; ++d0) kf[d0 - D0A] = *(const LAS bf16x8*)(Ks + half * (32 * DQK * 2) + kswz<DQK>(r32, (d0 * 16 + hi * 8) * 2));
; }
; template <int D0A, int D0B> DI void qk_mma(f32x16& p, const bf16x8* kf, const bf16x8* qr) {
; #pragma unroll
;     for (int d0 = D0A; d0 < D0B; ++d0) {
.LBB0_1982:
	s_and_b32 s1, s43, 3
	s_mulk_i32 s1, 0x6000
	s_add_i32 s1, s49, s1
	s_waitcnt vmcnt(5)
	s_barrier
	v_lshl_add_u64 v[174:175], s[34:35], 0, v[136:137]
	s_mov_b32 m0, s1
	s_mov_b32 s0, s5
	s_mov_b32 s5, s44
	s_mov_b32 s44, s4
	v_lshl_add_u64 v[176:177], s[34:35], 0, v[138:139]
	s_lshl_b32 s4, s4, 14
	global_load_lds_dwordx4 v[174:175], off
	s_add_i32 m0, s1, 0x2000
	v_lshl_add_u64 v[178:179], s[34:35], 0, v[140:141]
	s_add_i32 s4, s52, s4
	global_load_lds_dwordx4 v[176:177], off
	s_add_i32 m0, s1, 0x4000
	v_lshl_add_u64 v[182:183], s[34:35], 0, v[144:145]
	s_add_i32 s6, s4, 0x400
	global_load_lds_dwordx4 v[178:179], off
	s_mov_b32 m0, s4
	v_lshl_add_u64 v[180:181], s[34:35], 0, v[142:143]
	global_load_lds_dwordx4 v[182:183], off
	s_mov_b32 m0, s6
	s_add_i32 s1, s43, -3
	global_load_lds_dwordx4 v[180:181], off
	s_and_b32 s1, s1, 3
	s_mulk_i32 s1, 0x6000
	v_add_u32_e32 v246, s1, v158
	v_add_u32_e32 v174, v246, v151
	v_add_u32_e32 v178, v246, v149
	v_add_u32_e32 v182, v246, v148
	v_add_u32_e32 v186, v246, v147
	v_add_u32_e32 v190, v246, v146
	v_add_u32_e32 v194, v246, v150
	s_lshl_b32 s1, s0, 14
	ds_read_b128 v[174:177], v174 offset:12288
	ds_read_b128 v[178:181], v178 offset:12288
	ds_read_b128 v[182:185], v182 offset:12288
	ds_read_b128 v[186:189], v186 offset:12288
	ds_read_b128 v[190:193], v190 offset:12288
	ds_read_b128 v[194:197], v194 offset:12288
	v_add_u32_e32 v254, s1, v130
	ds_read_b64_tr_b16 v[198:199], v254 offset:0
	ds_read_b64_tr_b16 v[200:201], v254 offset:0x800
	ds_read_b64_tr_b16 v[202:203], v254 offset:0x1000
	ds_read_b64_tr_b16 v[204:205], v254 offset:0x1800
	ds_read_b64_tr_b16 v[206:207], v254 offset:0x200
	ds_read_b64_tr_b16 v[208:209], v254 offset:0xa00
	ds_read_b64_tr_b16 v[210:211], v254 offset:0x1200
	ds_read_b64_tr_b16 v[212:213], v254 offset:0x1a00
	ds_read_b64_tr_b16 v[214:215], v254 offset:0x400
	ds_read_b64_tr_b16 v[216:217], v254 offset:0xc00
	ds_read_b64_tr_b16 v[218:219], v254 offset:0x1400
	ds_read_b64_tr_b16 v[220:221], v254 offset:0x1c00
	ds_read_b64_tr_b16 v[222:223], v254 offset:0x600
	ds_read_b64_tr_b16 v[224:225], v254 offset:0xe00
	ds_read_b64_tr_b16 v[226:227], v254 offset:0x1600
	ds_read_b64_tr_b16 v[228:229], v254 offset:0x1e00
	s_setprio 1
	v_exp_f32_e32 v64, v64
	v_exp_f32_e32 v65, v65
	v_exp_f32_e32 v66, v66
	v_exp_f32_e32 v67, v67
	v_exp_f32_e32 v68, v68
	v_add_f32_e32 v230, 0, v64
	v_exp_f32_e32 v69, v69
	v_add_f32_e32 v230, v65, v230
	v_exp_f32_e32 v70, v70
	v_add_f32_e32 v230, v66, v230
	v_exp_f32_e32 v71, v71
	v_add_f32_e32 v230, v67, v230
	v_exp_f32_e32 v72, v72
	v_add_f32_e32 v230, v68, v230
	v_exp_f32_e32 v73, v73
	v_add_f32_e32 v230, v69, v230
	v_exp_f32_e32 v74, v74
	v_add_f32_e32 v230, v70, v230
	v_exp_f32_e32 v75, v75
	v_add_f32_e32 v230, v71, v230
	v_exp_f32_e32 v76, v76
	v_add_f32_e32 v230, v72, v230
	v_exp_f32_e32 v77, v77
	v_add_f32_e32 v230, v73, v230
	v_exp_f32_e32 v78, v78
	v_add_f32_e32 v230, v74, v230
	v_exp_f32_e32 v79, v79
	v_add_f32_e32 v230, v75, v230
	v_add_f32_e32 v230, v76, v230
	v_add_f32_e32 v230, v77, v230
	v_add_f32_e32 v230, v78, v230
	v_add_f32_e32 v230, v79, v230
	v_add_f32_e32 v173, v173, v230
	v_cvt_pk_bf16_f32 v64, v64, v65
	v_cvt_pk_bf16_f32 v65, v66, v67
	v_cvt_pk_bf16_f32 v66, v68, v69
	v_cvt_pk_bf16_f32 v67, v70, v71
	v_cvt_pk_bf16_f32 v68, v72, v73
	v_cvt_pk_bf16_f32 v69, v74, v75
	v_cvt_pk_bf16_f32 v70, v76, v77
	v_cvt_pk_bf16_f32 v71, v78, v79
	s_nop 0
	v_permlane32_swap_b32_e32 v64, v66
	v_permlane32_swap_b32_e32 v65, v67
	v_permlane32_swap_b32_e32 v68, v70
	v_permlane32_swap_b32_e32 v69, v71
	s_waitcnt lgkmcnt(0)
	v_add_u32_e32 v72, v246, v152
	v_add_u32_e32 v73, v246, v153
	ds_read_b128 v[230:233], v72 offset:12288
	ds_read_b128 v[234:237], v73 offset:12288
	v_add_u32_e32 v72, v246, v154
	v_add_u32_e32 v73, v246, v155
	ds_read_b128 v[238:241], v72 offset:12288
	ds_read_b128 v[242:245], v73 offset:12288
	v_add_u32_e32 v72, v246, v156
	v_add_u32_e32 v73, v246, v157
	ds_read_b128 v[246:249], v72 offset:12288
	ds_read_b128 v[250:253], v73 offset:12288
	s_setprio 0
	v_mfma_f32_32x32x16_bf16 v[48:63], v[64:67], v[198:201], v[48:63]
	v_mfma_f32_32x32x16_bf16 v[32:47], v[64:67], v[206:209], v[32:47]
	v_mfma_f32_32x32x16_bf16 v[16:31], v[64:67], v[214:217], v[16:31]
	v_mfma_f32_32x32x16_bf16 v[0:15], v[64:67], v[222:225], v[0:15]
	v_mfma_f32_32x32x16_bf16 v[48:63], v[68:71], v[202:205], v[48:63]
	v_mfma_f32_32x32x16_bf16 v[32:47], v[68:71], v[210:213], v[32:47]
	v_mfma_f32_32x32x16_bf16 v[16:31], v[68:71], v[218:221], v[16:31]
	v_mfma_f32_32x32x16_bf16 v[0:15], v[68:71], v[226:229], v[0:15]
	s_waitcnt lgkmcnt(0)
	v_mfma_f32_32x32x16_bf16 v[64:79], v[174:177], v[80:83], 0
	v_mfma_f32_32x32x16_bf16 v[64:79], v[178:181], v[84:87], v[64:79]
	v_mfma_f32_32x32x16_bf16 v[64:79], v[182:185], v[88:91], v[64:79]
	v_mfma_f32_32x32x16_bf16 v[64:79], v[186:189], v[92:95], v[64:79]
	v_mfma_f32_32x32x16_bf16 v[64:79], v[190:193], v[96:99], v[64:79]
	v_mfma_f32_32x32x16_bf16 v[64:79], v[194:197], v[100:103], v[64:79]
	s_waitcnt lgkmcnt(0)
; #define LAS __attribute__((address_space(3)))
; DI void expsum(f32x16& p, float& l_reg, bf16x8& pa0, bf16x8& pa1) {
; #pragma unroll
;     for (int r = 0; r < 16; ++r) p[r] = __builtin_amdgcn_exp2f(p[r]);
;     float ps = 0.f;
; #pragma unroll
;     for (int r = 0; r < 16; ++r) ps += p[r];
;     l_reg += ps; asm volatile("" : "+v"(l_reg));
;     ...
;     ATT_PK4(p, 0, pa0); ATT_PK4(p, 8, pa1);
;     ...
; }
; DI int v_rd_base(int lane) { return ((lane & 3) << 3) | (((lane >> 2) & 3) << 6) | (((lane >> 4) & 1) << 5) | (((lane >> 5) & 1) << 8); }
; template <int OFF> DI s16x4 tr_read(int vb) { s16x4 r; asm volatile("ds_read_b64_tr_b16 %0, %1 offset:%2" : "=&v"(r) : "v"(vb), "i"(OFF) : "memory"); return r; }
; template <int H> DI void v_reads(s16x4* vf, int vb) {
;     vf[0] = tr_read<v_rd_off(0, 2 * H, 0)>(vb); vf[1] = tr_read<v_rd_off(0, 2 * H, 1)>(vb); vf[2] = tr_read<v_rd_off(0, 2 * H + 1, 0)>(vb); vf[3] = tr_read<v_rd_off(0, 2 * H + 1, 1)>(vb);
;     vf[4] = tr_read<v_rd_off(1, 2 * H, 0)>(vb); vf[5] = tr_read<v_rd_off(1, 2 * H, 1)>(vb); vf[6] = tr_read<v_rd_off(1, 2 * H + 1, 0)>(vb); vf[7] = tr_read<v_rd_off(1, 2 * H + 1, 1)>(vb);
;     vf[8] = tr_read<v_rd_off(2, 2 * H, 0)>(vb); vf[9] = tr_read<v_rd_off(2, 2 * H, 1)>(vb); vf[10] = tr_read<v_rd_off(2, 2 * H + 1, 0)>(vb); vf[11] = tr_read<v_rd_off(2, 2 * H + 1, 1)>(vb);
;     vf[12] = tr_read<v_rd_off(3, 2 * H, 0)>(vb); vf[13] = tr_read<v_rd_off(3, 2 * H, 1)>(vb); vf[14] = tr_read<v_rd_off(3, 2 * H + 1, 0)>(vb); vf[15] = tr_read<v_rd_off(3, 2 * H + 1, 1)>(vb);
; }
; DI void pv_mma(f32x16* o, const s16x4* vf, bf16x8 pa0, bf16x8 pa1) {
;     ...
; #pragma unroll
;     for (int d0 = 0; d0 < 4; ++d0) {
;         o[d0] = __builtin_amdgcn_mfma_f32_32x32x16_bf16(pa0, ATT_PK(vf[4 * d0], vf[4 * d0 + 1]), o[d0], 0, 0, 0);
;         o[d0] = __builtin_amdgcn_mfma_f32_32x32x16_bf16(pa1, ATT_PK(vf[4 * d0 + 2], vf[4 * d0 + 3]), o[d0], 0, 0, 0); }
;     ...
; }
; template <int DQK, int D0A, int D0B> DI void k_reads(bf16x8* kf, const LAS unsigned char* Ks, int half, int r32, int hi) {
; #pragma unroll
;     for (int d0 = D0A; d0 < D0B; ++d0) kf[d0 - D0A] = *(const LAS bf16x8*)(Ks + half * (32 * DQK * 2) + kswz<DQK>(r32, (d0 * 16 + hi * 8) * 2));
; }
; template <int D0A, int D0B> DI void qk_mma(f32x16& p, const bf16x8* kf, const bf16x8* qr) {
; #pragma unroll
;     for (int d0 = D0A; d0 < D0B; ++d0) {
	v_mfma_f32_32x32x16_bf16 v[64:79], v[230:233], v[104:107], v[64:79]
	v_mfma_f32_32x32x16_bf16 v[64:79], v[234:237], v[108:111], v[64:79]
	v_mfma_f32_32x32x16_bf16 v[64:79], v[238:241], v[112:115], v[64:79]
	v_mfma_f32_32x32x16_bf16 v[64:79], v[242:245], v[116:119], v[64:79]
	v_mfma_f32_32x32x16_bf16 v[64:79], v[246:249], v[120:123], v[64:79]
	v_mfma_f32_32x32x16_bf16 v[64:79], v[250:253], v[124:127], v[64:79]
	s_add_i32 s4, s43, -2
	s_and_b32 s4, s4, 3
	s_mulk_i32 s4, 0x6000
	v_add_u32_e32 v246, s4, v158
	v_add_u32_e32 v174, v246, v151
	v_add_u32_e32 v178, v246, v149
	v_add_u32_e32 v182, v246, v148
	v_add_u32_e32 v186, v246, v147
	v_add_u32_e32 v190, v246, v146
	v_add_u32_e32 v194, v246, v150
	ds_read_b128 v[174:177], v174
	ds_read_b128 v[178:181], v178
	ds_read_b128 v[182:185], v182
	ds_read_b128 v[186:189], v186
	ds_read_b128 v[190:193], v190
	ds_read_b128 v[194:197], v194
	ds_read_b64_tr_b16 v[198:199], v254 offset:0x2000
	ds_read_b64_tr_b16 v[200:201], v254 offset:0x2800
	ds_read_b64_tr_b16 v[202:203], v254 offset:0x3000
	ds_read_b64_tr_b16 v[204:205], v254 offset:0x3800
	ds_read_b64_tr_b16 v[206:207], v254 offset:0x2200
	ds_read_b64_tr_b16 v[208:209], v254 offset:0x2a00
	ds_read_b64_tr_b16 v[210:211], v254 offset:0x3200
	ds_read_b64_tr_b16 v[212:213], v254 offset:0x3a00
	ds_read_b64_tr_b16 v[214:215], v254 offset:0x2400
	ds_read_b64_tr_b16 v[216:217], v254 offset:0x2c00
	ds_read_b64_tr_b16 v[218:219], v254 offset:0x3400
	ds_read_b64_tr_b16 v[220:221], v254 offset:0x3c00
	ds_read_b64_tr_b16 v[222:223], v254 offset:0x2600
	ds_read_b64_tr_b16 v[224:225], v254 offset:0x2e00
	ds_read_b64_tr_b16 v[226:227], v254 offset:0x3600
	ds_read_b64_tr_b16 v[228:229], v254 offset:0x3e00
	s_setprio 1
	v_exp_f32_e32 v64, v64
	v_exp_f32_e32 v65, v65
	v_exp_f32_e32 v66, v66
	v_exp_f32_e32 v67, v67
	v_exp_f32_e32 v68, v68
	v_add_f32_e32 v230, 0, v64
	v_exp_f32_e32 v69, v69
	v_add_f32_e32 v230, v65, v230
	v_exp_f32_e32 v70, v70
	v_add_f32_e32 v230, v66, v230
	v_exp_f32_e32 v71, v71
	v_add_f32_e32 v230, v67, v230
	v_exp_f32_e32 v72, v72
	v_add_f32_e32 v230, v68, v230
	v_exp_f32_e32 v73, v73
	v_add_f32_e32 v230, v69, v230
	v_exp_f32_e32 v74, v74
	v_add_f32_e32 v230, v70, v230
	v_exp_f32_e32 v75, v75
	v_add_f32_e32 v230, v71, v230
	v_exp_f32_e32 v76, v76
	v_add_f32_e32 v230, v72, v230
	v_exp_f32_e32 v77, v77
	v_add_f32_e32 v230, v73, v230
	v_exp_f32_e32 v78, v78
	v_add_f32_e32 v230, v74, v230
	v_exp_f32_e32 v79, v79
	v_add_f32_e32 v230, v75, v230
	v_add_f32_e32 v230, v76, v230
	v_add_f32_e32 v230, v77, v230
	v_add_f32_e32 v230, v78, v230
	v_add_f32_e32 v230, v79, v230
	v_add_f32_e32 v173, v173, v230
	v_cvt_pk_bf16_f32 v64, v64, v65
	v_cvt_pk_bf16_f32 v65, v66, v67
	v_cvt_pk_bf16_f32 v66, v68, v69
	v_cvt_pk_bf16_f32 v67, v70, v71
	v_cvt_pk_bf16_f32 v68, v72, v73
	v_cvt_pk_bf16_f32 v69, v74, v75
	v_cvt_pk_bf16_f32 v70, v76, v77
	v_cvt_pk_bf16_f32 v71, v78, v79
	s_nop 0
	v_permlane32_swap_b32_e32 v64, v66
	v_permlane32_swap_b32_e32 v65, v67
	v_permlane32_swap_b32_e32 v68, v70
	v_permlane32_swap_b32_e32 v69, v71
	s_waitcnt lgkmcnt(0)
	v_add_u32_e32 v72, v246, v152
	v_add_u32_e32 v73, v246, v153
	ds_read_b128 v[230:233], v72
	ds_read_b128 v[234:237], v73
	v_add_u32_e32 v72, v246, v154
	v_add_u32_e32 v73, v246, v155
	ds_read_b128 v[238:241], v72
	ds_read_b128 v[242:245], v73
	v_add_u32_e32 v72, v246, v156
	v_add_u32_e32 v73, v246, v157
	ds_read_b128 v[246:249], v72
	ds_read_b128 v[250:253], v73
	s_setprio 0
	v_mfma_f32_32x32x16_bf16 v[48:63], v[64:67], v[198:201], v[48:63]
	v_mfma_f32_32x32x16_bf16 v[32:47], v[64:67], v[206:209], v[32:47]
	v_mfma_f32_32x32x16_bf16 v[16:31], v[64:67], v[214:217], v[16:31]
	v_mfma_f32_32x32x16_bf16 v[0:15], v[64:67], v[222:225], v[0:15]
	v_mfma_f32_32x32x16_bf16 v[48:63], v[68:71], v[202:205], v[48:63]
	v_mfma_f32_32x32x16_bf16 v[32:47], v[68:71], v[210:213], v[32:47]
	v_mfma_f32_32x32x16_bf16 v[16:31], v[68:71], v[218:221], v[16:31]
	v_mfma_f32_32x32x16_bf16 v[0:15], v[68:71], v[226:229], v[0:15]
	s_waitcnt lgkmcnt(0)
	v_mfma_f32_32x32x16_bf16 v[64:79], v[174:177], v[80:83], 0
	v_mfma_f32_32x32x16_bf16 v[64:79], v[178:181], v[84:87], v[64:79]
	v_mfma_f32_32x32x16_bf16 v[64:79], v[182:185], v[88:91], v[64:79]
	v_mfma_f32_32x32x16_bf16 v[64:79], v[186:189], v[92:95], v[64:79]
	v_mfma_f32_32x32x16_bf16 v[64:79], v[190:193], v[96:99], v[64:79]
	v_mfma_f32_32x32x16_bf16 v[64:79], v[194:197], v[100:103], v[64:79]
	s_waitcnt lgkmcnt(0)
	v_mfma_f32_32x32x16_bf16 v[64:79], v[230:233], v[104:107], v[64:79]
	v_mfma_f32_32x32x16_bf16 v[64:79], v[234:237], v[108:111], v[64:79]
	v_mfma_f32_32x32x16_bf16 v[64:79], v[238:241], v[112:115], v[64:79]
	v_mfma_f32_32x32x16_bf16 v[64:79], v[242:245], v[116:119], v[64:79]
	v_mfma_f32_32x32x16_bf16 v[64:79], v[246:249], v[120:123], v[64:79]
	v_mfma_f32_32x32x16_bf16 v[64:79], v[250:253], v[124:127], v[64:79]
	s_add_i32 s43, s43, 1
	v_lshl_add_u64 v[136:137], v[136:137], 0, s[36:37]
	v_lshl_add_u64 v[138:139], v[138:139], 0, s[36:37]
	v_lshl_add_u64 v[140:141], v[140:141], 0, s[36:37]
	v_lshl_add_u64 v[142:143], v[142:143], 0, s[38:39]
	v_lshl_add_u64 v[144:145], v[144:145], 0, s[38:39]
	s_cmp_eq_u32 s43, 64
	s_mov_b32 s4, s0
	s_cbranch_scc0 .LBB0_1982
	s_lshl_b32 s0, s55, 2
	s_add_i32 s4, s0, 0
	s_add_i32 s6, s52, s1
	s_add_i32 s4, s4, 0x24000
	s_add_i32 s7, s6, 0x400
	s_add_u32 s0, s2, 0x3f0000
	s_addc_u32 s1, s3, 0
	s_waitcnt vmcnt(5)
	s_barrier
; #define LAS __attribute__((address_space(3)))
; DI void expsum(f32x16& p, float& l_reg, bf16x8& pa0, bf16x8& pa1) {
; #pragma unroll
;     for (int r = 0; r < 16; ++r) p[r] = __builtin_amdgcn_exp2f(p[r]);
;     float ps = 0.f;
; #pragma unroll
;     for (int r = 0; r < 16; ++r) ps += p[r];
;     l_reg += ps; asm volatile("" : "+v"(l_reg));
;     ...
;     ATT_PK4(p, 0, pa0); ATT_PK4(p, 8, pa1);
;     ...
; }
; DI int v_rd_base(int lane) { return ((lane & 3) << 3) | (((lane >> 2) & 3) << 6) | (((lane >> 4) & 1) << 5) | (((lane >> 5) & 1) << 8); }
; template <int OFF> DI s16x4 tr_read(int vb) { s16x4 r; asm volatile("ds_read_b64_tr_b16 %0, %1 offset:%2" : "=&v"(r) : "v"(vb), "i"(OFF) : "memory"); return r; }
; template <int H> DI void v_reads(s16x4* vf, int vb) {
;     vf[0] = tr_read<v_rd_off(0, 2 * H, 0)>(vb); vf[1] = tr_read<v_rd_off(0, 2 * H, 1)>(vb); vf[2] = tr_read<v_rd_off(0, 2 * H + 1, 0)>(vb); vf[3] = tr_read<v_rd_off(0, 2 * H + 1, 1)>(vb);
;     vf[4] = tr_read<v_rd_off(1, 2 * H, 0)>(vb); vf[5] = tr_read<v_rd_off(1, 2 * H, 1)>(vb); vf[6] = tr_read<v_rd_off(1, 2 * H + 1, 0)>(vb); vf[7] = tr_read<v_rd_off(1, 2 * H + 1, 1)>(vb);
;     vf[8] = tr_read<v_rd_off(2, 2 * H, 0)>(vb); vf[9] = tr_read<v_rd_off(2, 2 * H, 1)>(vb); vf[10] = tr_read<v_rd_off(2, 2 * H + 1, 0)>(vb); vf[11] = tr_read<v_rd_off(2, 2 * H + 1, 1)>(vb);
;     vf[12] = tr_read<v_rd_off(3, 2 * H, 0)>(vb); vf[13] = tr_read<v_rd_off(3, 2 * H, 1)>(vb); vf[14] = tr_read<v_rd_off(3, 2 * H + 1, 0)>(vb); vf[15] = tr_read<v_rd_off(3, 2 * H + 1, 1)>(vb);
; }
; DI void pv_mma(f32x16* o, const s16x4* vf, bf16x8 pa0, bf16x8 pa1) {
;     ...
; #pragma unroll
;     for (int d0 = 0; d0 < 4; ++d0) {
;         o[d0] = __builtin_amdgcn_mfma_f32_32x32x16_bf16(pa0, ATT_PK(vf[4 * d0], vf[4 * d0 + 1]), o[d0], 0, 0, 0);
;         o[d0] = __builtin_amdgcn_mfma_f32_32x32x16_bf16(pa1, ATT_PK(vf[4 * d0 + 2], vf[4 * d0 + 3]), o[d0], 0, 0, 0); }
;     ...
; }
; template <int DQK, int D0A, int D0B> DI void k_reads(bf16x8* kf, const LAS unsigned char* Ks, int half, int r32, int hi) {
; #pragma unroll
;     for (int d0 = D0A; d0 < D0B; ++d0) kf[d0 - D0A] = *(const LAS bf16x8*)(Ks + half * (32 * DQK * 2) + kswz<DQK>(r32, (d0 * 16 + hi * 8) * 2));
; }
; template <int D0A, int D0B> DI void qk_mma(f32x16& p, const bf16x8* kf, const bf16x8* qr) {
; #pragma unroll
;     for (int d0 = D0A; d0 < D0B; ++d0) {
	v_lshl_add_u64 v[132:133], v[132:133], 1, s[0:1]
	s_mov_b32 m0, s6
	v_lshl_add_u64 v[134:135], v[134:135], 1, s[0:1]
	global_load_lds_dwordx4 v[132:133], off
	s_mov_b32 m0, s7
	s_nop 0
	global_load_lds_dwordx4 v[134:135], off
	ds_read_b128 v[132:135], v161 offset:36864
	ds_read_b128 v[136:139], v162 offset:36864
	ds_read_b128 v[140:143], v163 offset:36864
	ds_read_b128 v[174:177], v164 offset:36864
	ds_read_b128 v[178:181], v165 offset:36864
	ds_read_b128 v[182:185], v166 offset:36864
	v_lshl_add_u32 v144, s5, 14, v130
	ds_read_b64_tr_b16 v[186:187], v144 offset:0
	ds_read_b64_tr_b16 v[188:189], v144 offset:0x800
	ds_read_b64_tr_b16 v[190:191], v144 offset:0x1000
	ds_read_b64_tr_b16 v[192:193], v144 offset:0x1800
	ds_read_b64_tr_b16 v[194:195], v144 offset:0x200
	ds_read_b64_tr_b16 v[196:197], v144 offset:0xa00
	ds_read_b64_tr_b16 v[198:199], v144 offset:0x1200
	ds_read_b64_tr_b16 v[200:201], v144 offset:0x1a00
	ds_read_b64_tr_b16 v[202:203], v144 offset:0x400
	ds_read_b64_tr_b16 v[204:205], v144 offset:0xc00
	ds_read_b64_tr_b16 v[206:207], v144 offset:0x1400
	ds_read_b64_tr_b16 v[208:209], v144 offset:0x1c00
	ds_read_b64_tr_b16 v[210:211], v144 offset:0x600
	ds_read_b64_tr_b16 v[212:213], v144 offset:0xe00
	ds_read_b64_tr_b16 v[214:215], v144 offset:0x1600
	ds_read_b64_tr_b16 v[216:217], v144 offset:0x1e00
	s_setprio 1
	v_exp_f32_e32 v64, v64
	v_exp_f32_e32 v65, v65
	v_exp_f32_e32 v66, v66
	v_exp_f32_e32 v67, v67
	v_exp_f32_e32 v68, v68
	v_add_f32_e32 v145, 0, v64
	v_exp_f32_e32 v69, v69
	v_add_f32_e32 v145, v65, v145
	v_exp_f32_e32 v70, v70
	v_add_f32_e32 v145, v66, v145
	v_exp_f32_e32 v71, v71
	v_add_f32_e32 v145, v67, v145
	v_exp_f32_e32 v72, v72
	v_add_f32_e32 v145, v68, v145
	v_exp_f32_e32 v73, v73
	v_add_f32_e32 v145, v69, v145
	v_exp_f32_e32 v74, v74
	v_add_f32_e32 v145, v70, v145
	v_exp_f32_e32 v75, v75
	v_add_f32_e32 v145, v71, v145
	v_exp_f32_e32 v76, v76
	v_add_f32_e32 v145, v72, v145
	v_exp_f32_e32 v77, v77
	v_add_f32_e32 v145, v73, v145
	v_exp_f32_e32 v78, v78
	v_add_f32_e32 v145, v74, v145
	v_exp_f32_e32 v79, v79
	v_add_f32_e32 v145, v75, v145
	v_add_f32_e32 v145, v76, v145
	v_add_f32_e32 v145, v77, v145
	v_add_f32_e32 v145, v78, v145
	v_add_f32_e32 v145, v79, v145
	v_add_f32_e32 v145, v173, v145
	v_cvt_pk_bf16_f32 v64, v64, v65
	v_cvt_pk_bf16_f32 v65, v66, v67
	v_cvt_pk_bf16_f32 v66, v68, v69
	v_cvt_pk_bf16_f32 v67, v70, v71
	v_cvt_pk_bf16_f32 v68, v72, v73
	v_cvt_pk_bf16_f32 v69, v74, v75
	v_cvt_pk_bf16_f32 v70, v76, v77
	v_cvt_pk_bf16_f32 v71, v78, v79
	s_nop 0
	v_permlane32_swap_b32_e32 v64, v66
	v_permlane32_swap_b32_e32 v65, v67
	v_permlane32_swap_b32_e32 v68, v70
	v_permlane32_swap_b32_e32 v69, v71
	s_waitcnt lgkmcnt(0)
	ds_read_b128 v[218:221], v167 offset:36864
	ds_read_b128 v[222:225], v168 offset:36864
	ds_read_b128 v[226:229], v169 offset:36864
	ds_read_b128 v[230:233], v170 offset:36864
	ds_read_b128 v[234:237], v171 offset:36864
	ds_read_b128 v[238:241], v172 offset:36864
	s_setprio 0
	v_mfma_f32_32x32x16_bf16 v[48:63], v[64:67], v[186:189], v[48:63]
	v_mfma_f32_32x32x16_bf16 v[32:47], v[64:67], v[194:197], v[32:47]
	v_mfma_f32_32x32x16_bf16 v[16:31], v[64:67], v[202:205], v[16:31]
	v_mfma_f32_32x32x16_bf16 v[0:15], v[64:67], v[210:213], v[0:15]
	v_mfma_f32_32x32x16_bf16 v[48:63], v[68:71], v[190:193], v[48:63]
	v_mfma_f32_32x32x16_bf16 v[32:47], v[68:71], v[198:201], v[32:47]
	v_mfma_f32_32x32x16_bf16 v[16:31], v[68:71], v[206:209], v[16:31]
	v_mfma_f32_32x32x16_bf16 v[0:15], v[68:71], v[214:217], v[0:15]
	s_waitcnt lgkmcnt(0)
	v_mfma_f32_32x32x16_bf16 v[64:79], v[132:135], v[80:83], 0
	v_mfma_f32_32x32x16_bf16 v[64:79], v[136:139], v[84:87], v[64:79]
	v_mfma_f32_32x32x16_bf16 v[64:79], v[140:143], v[88:91], v[64:79]
	v_mfma_f32_32x32x16_bf16 v[64:79], v[174:177], v[92:95], v[64:79]
	v_mfma_f32_32x32x16_bf16 v[64:79], v[178:181], v[96:99], v[64:79]
	v_mfma_f32_32x32x16_bf16 v[64:79], v[182:185], v[100:103], v[64:79]
	s_waitcnt lgkmcnt(0)
	v_mfma_f32_32x32x16_bf16 v[64:79], v[218:221], v[104:107], v[64:79]
	v_mfma_f32_32x32x16_bf16 v[64:79], v[222:225], v[108:111], v[64:79]
	v_mfma_f32_32x32x16_bf16 v[64:79], v[226:229], v[112:115], v[64:79]
	v_mfma_f32_32x32x16_bf16 v[64:79], v[230:233], v[116:119], v[64:79]
	v_mfma_f32_32x32x16_bf16 v[64:79], v[234:237], v[120:123], v[64:79]
	v_mfma_f32_32x32x16_bf16 v[64:79], v[238:241], v[124:127], v[64:79]
	ds_read_b128 v[132:135], v161 offset:49152
	ds_read_b128 v[136:139], v162 offset:49152
	ds_read_b128 v[140:143], v163 offset:49152
	ds_read_b128 v[174:177], v164 offset:49152
	ds_read_b128 v[178:181], v165 offset:49152
	ds_read_b128 v[182:185], v166 offset:49152
	ds_read_b64_tr_b16 v[186:187], v144 offset:0x2000
	ds_read_b64_tr_b16 v[188:189], v144 offset:0x2800
	ds_read_b64_tr_b16 v[190:191], v144 offset:0x3000
	ds_read_b64_tr_b16 v[192:193], v144 offset:0x3800
	ds_read_b64_tr_b16 v[194:195], v144 offset:0x2200
	ds_read_b64_tr_b16 v[196:197], v144 offset:0x2a00
	ds_read_b64_tr_b16 v[198:199], v144 offset:0x3200
	ds_read_b64_tr_b16 v[200:201], v144 offset:0x3a00
	ds_read_b64_tr_b16 v[202:203], v144 offset:0x2400
	ds_read_b64_tr_b16 v[204:205], v144 offset:0x2c00
	ds_read_b64_tr_b16 v[206:207], v144 offset:0x3400
	ds_read_b64_tr_b16 v[208:209], v144 offset:0x3c00
	ds_read_b64_tr_b16 v[210:211], v144 offset:0x2600
	ds_read_b64_tr_b16 v[212:213], v144 offset:0x2e00
	ds_read_b64_tr_b16 v[214:215], v144 offset:0x3600
	ds_read_b64_tr_b16 v[216:217], v144 offset:0x3e00
	s_nop 5
	s_setprio 1
	v_exp_f32_e32 v64, v64
	v_exp_f32_e32 v65, v65
	v_exp_f32_e32 v66, v66
	v_exp_f32_e32 v67, v67
	v_exp_f32_e32 v68, v68
	v_add_f32_e32 v144, 0, v64
	v_exp_f32_e32 v69, v69
	v_add_f32_e32 v144, v65, v144
	v_exp_f32_e32 v70, v70
	v_add_f32_e32 v144, v66, v144
	v_exp_f32_e32 v71, v71
	v_add_f32_e32 v144, v67, v144
	v_exp_f32_e32 v72, v72
	v_add_f32_e32 v144, v68, v144
	v_exp_f32_e32 v73, v73
	v_add_f32_e32 v144, v69, v144
	v_exp_f32_e32 v74, v74
	v_add_f32_e32 v144, v70, v144
	v_exp_f32_e32 v75, v75
	v_add_f32_e32 v144, v71, v144
	v_exp_f32_e32 v76, v76
	v_add_f32_e32 v144, v72, v144
	v_exp_f32_e32 v77, v77
	v_add_f32_e32 v144, v73, v144
	v_exp_f32_e32 v78, v78
	v_add_f32_e32 v144, v74, v144
	v_exp_f32_e32 v79, v79
	v_add_f32_e32 v144, v75, v144
	v_add_f32_e32 v144, v76, v144
	v_add_f32_e32 v144, v77, v144
	v_add_f32_e32 v144, v78, v144
	v_add_f32_e32 v144, v79, v144
	v_add_f32_e32 v144, v145, v144
	v_cvt_pk_bf16_f32 v64, v64, v65
	v_cvt_pk_bf16_f32 v65, v66, v67
	v_cvt_pk_bf16_f32 v66, v68, v69
	v_cvt_pk_bf16_f32 v67, v70, v71
	v_cvt_pk_bf16_f32 v68, v72, v73
	v_cvt_pk_bf16_f32 v69, v74, v75
	v_cvt_pk_bf16_f32 v70, v76, v77
	v_cvt_pk_bf16_f32 v71, v78, v79
	s_nop 0
	v_permlane32_swap_b32_e32 v64, v66
	v_permlane32_swap_b32_e32 v65, v67
	v_permlane32_swap_b32_e32 v68, v70
	v_permlane32_swap_b32_e32 v69, v71
	s_waitcnt lgkmcnt(0)
; #define LAS __attribute__((address_space(3)))
; DI void expsum(f32x16& p, float& l_reg, bf16x8& pa0, bf16x8& pa1) {
; #pragma unroll
;     for (int r = 0; r < 16; ++r) p[r] = __builtin_amdgcn_exp2f(p[r]);
;     float ps = 0.f;
; #pragma unroll
;     for (int r = 0; r < 16; ++r) ps += p[r];
;     l_reg += ps; asm volatile("" : "+v"(l_reg));
;     ...
;     ATT_PK4(p, 0, pa0); ATT_PK4(p, 8, pa1);
;     ...
; }
; DI int v_rd_base(int lane) { return ((lane & 3) << 3) | (((lane >> 2) & 3) << 6) | (((lane >> 4) & 1) << 5) | (((lane >> 5) & 1) << 8); }
; template <int OFF> DI s16x4 tr_read(int vb) { s16x4 r; asm volatile("ds_read_b64_tr_b16 %0, %1 offset:%2" : "=&v"(r) : "v"(vb), "i"(OFF) : "memory"); return r; }
; template <int H> DI void v_reads(s16x4* vf, int vb) {
;     vf[0] = tr_read<v_rd_off(0, 2 * H, 0)>(vb); vf[1] = tr_read<v_rd_off(0, 2 * H, 1)>(vb); vf[2] = tr_read<v_rd_off(0, 2 * H + 1, 0)>(vb); vf[3] = tr_read<v_rd_off(0, 2 * H + 1, 1)>(vb);
;     vf[4] = tr_read<v_rd_off(1, 2 * H, 0)>(vb); vf[5] = tr_read<v_rd_off(1, 2 * H, 1)>(vb); vf[6] = tr_read<v_rd_off(1, 2 * H + 1, 0)>(vb); vf[7] = tr_read<v_rd_off(1, 2 * H + 1, 1)>(vb);
;     vf[8] = tr_read<v_rd_off(2, 2 * H, 0)>(vb); vf[9] = tr_read<v_rd_off(2, 2 * H, 1)>(vb); vf[10] = tr_read<v_rd_off(2, 2 * H + 1, 0)>(vb); vf[11] = tr_read<v_rd_off(2, 2 * H + 1, 1)>(vb);
;     vf[12] = tr_read<v_rd_off(3, 2 * H, 0)>(vb); vf[13] = tr_read<v_rd_off(3, 2 * H, 1)>(vb); vf[14] = tr_read<v_rd_off(3, 2 * H + 1, 0)>(vb); vf[15] = tr_read<v_rd_off(3, 2 * H + 1, 1)>(vb);
; }
; DI void pv_mma(f32x16* o, const s16x4* vf, bf16x8 pa0, bf16x8 pa1) {
;     ...
; #pragma unroll
;     for (int d0 = 0; d0 < 4; ++d0) {
;         o[d0] = __builtin_amdgcn_mfma_f32_32x32x16_bf16(pa0, ATT_PK(vf[4 * d0], vf[4 * d0 + 1]), o[d0], 0, 0, 0);
;         o[d0] = __builtin_amdgcn_mfma_f32_32x32x16_bf16(pa1, ATT_PK(vf[4 * d0 + 2], vf[4 * d0 + 3]), o[d0], 0, 0, 0); }
;     ...
; }
; template <int DQK, int D0A, int D0B> DI void k_reads(bf16x8* kf, const LAS unsigned char* Ks, int half, int r32, int hi) {
; #pragma unroll
;     for (int d0 = D0A; d0 < D0B; ++d0) kf[d0 - D0A] = *(const LAS bf16x8*)(Ks + half * (32 * DQK * 2) + kswz<DQK>(r32, (d0 * 16 + hi * 8) * 2));
; }
; template <int D0A, int D0B> DI void qk_mma(f32x16& p, const bf16x8* kf, const bf16x8* qr) {
; #pragma unroll
;     for (int d0 = D0A; d0 < D0B; ++d0) {
	ds_read_b128 v[218:221], v167 offset:49152
	ds_read_b128 v[222:225], v168 offset:49152
	ds_read_b128 v[226:229], v169 offset:49152
	ds_read_b128 v[230:233], v170 offset:49152
	ds_read_b128 v[234:237], v171 offset:49152
	ds_read_b128 v[238:241], v172 offset:49152
	s_setprio 0
	v_mfma_f32_32x32x16_bf16 v[48:63], v[64:67], v[186:189], v[48:63]
	v_mfma_f32_32x32x16_bf16 v[32:47], v[64:67], v[194:197], v[32:47]
	v_mfma_f32_32x32x16_bf16 v[16:31], v[64:67], v[202:205], v[16:31]
	v_mfma_f32_32x32x16_bf16 v[0:15], v[64:67], v[210:213], v[0:15]
	v_mfma_f32_32x32x16_bf16 v[48:63], v[68:71], v[190:193], v[48:63]
	v_mfma_f32_32x32x16_bf16 v[32:47], v[68:71], v[198:201], v[32:47]
	v_mfma_f32_32x32x16_bf16 v[16:31], v[68:71], v[206:209], v[16:31]
	v_mfma_f32_32x32x16_bf16 v[0:15], v[68:71], v[214:217], v[0:15]
	s_waitcnt lgkmcnt(0)
	v_mfma_f32_32x32x16_bf16 v[64:79], v[132:135], v[80:83], 0
	v_mfma_f32_32x32x16_bf16 v[64:79], v[136:139], v[84:87], v[64:79]
	v_mfma_f32_32x32x16_bf16 v[64:79], v[140:143], v[88:91], v[64:79]
	v_mfma_f32_32x32x16_bf16 v[64:79], v[174:177], v[92:95], v[64:79]
	v_mfma_f32_32x32x16_bf16 v[64:79], v[178:181], v[96:99], v[64:79]
	v_mfma_f32_32x32x16_bf16 v[64:79], v[182:185], v[100:103], v[64:79]
	s_waitcnt lgkmcnt(0)
	v_mfma_f32_32x32x16_bf16 v[64:79], v[218:221], v[104:107], v[64:79]
	v_mfma_f32_32x32x16_bf16 v[64:79], v[222:225], v[108:111], v[64:79]
	v_mfma_f32_32x32x16_bf16 v[64:79], v[226:229], v[112:115], v[64:79]
	v_mfma_f32_32x32x16_bf16 v[64:79], v[230:233], v[116:119], v[64:79]
	v_mfma_f32_32x32x16_bf16 v[64:79], v[234:237], v[120:123], v[64:79]
	v_mfma_f32_32x32x16_bf16 v[64:79], v[238:241], v[124:127], v[64:79]
	s_waitcnt vmcnt(0)
	s_barrier
	ds_read_b128 v[132:135], v161 offset:61440
	ds_read_b128 v[136:139], v162 offset:61440
	ds_read_b128 v[140:143], v163 offset:61440
	ds_read_b128 v[174:177], v164 offset:61440
	ds_read_b128 v[162:165], v165 offset:61440
	ds_read_b128 v[178:181], v166 offset:61440
	v_add_u32_e32 v145, 0x8000, v130
	ds_read_b64_tr_b16 v[182:183], v145 offset:0
	ds_read_b64_tr_b16 v[184:185], v145 offset:0x800
	ds_read_b64_tr_b16 v[186:187], v145 offset:0x1000
	ds_read_b64_tr_b16 v[188:189], v145 offset:0x1800
	ds_read_b64_tr_b16 v[190:191], v145 offset:0x200
	ds_read_b64_tr_b16 v[192:193], v145 offset:0xa00
	ds_read_b64_tr_b16 v[194:195], v145 offset:0x1200
	ds_read_b64_tr_b16 v[196:197], v145 offset:0x1a00
	ds_read_b64_tr_b16 v[198:199], v145 offset:0x400
	ds_read_b64_tr_b16 v[200:201], v145 offset:0xc00
	ds_read_b64_tr_b16 v[202:203], v145 offset:0x1400
	ds_read_b64_tr_b16 v[204:205], v145 offset:0x1c00
	ds_read_b64_tr_b16 v[206:207], v145 offset:0x600
	ds_read_b64_tr_b16 v[208:209], v145 offset:0xe00
	ds_read_b64_tr_b16 v[210:211], v145 offset:0x1600
	ds_read_b64_tr_b16 v[212:213], v145 offset:0x1e00
	s_nop 3
	s_setprio 1
	v_exp_f32_e32 v64, v64
	v_exp_f32_e32 v65, v65
	v_exp_f32_e32 v66, v66
	v_exp_f32_e32 v67, v67
	v_exp_f32_e32 v68, v68
	v_add_f32_e32 v161, 0, v64
	v_exp_f32_e32 v69, v69
	v_add_f32_e32 v161, v65, v161
	v_exp_f32_e32 v70, v70
	v_add_f32_e32 v161, v66, v161
	v_exp_f32_e32 v71, v71
	v_add_f32_e32 v161, v67, v161
	v_exp_f32_e32 v72, v72
	v_add_f32_e32 v161, v68, v161
	v_exp_f32_e32 v73, v73
	v_add_f32_e32 v161, v69, v161
	v_exp_f32_e32 v74, v74
	v_add_f32_e32 v161, v70, v161
	v_exp_f32_e32 v75, v75
	v_add_f32_e32 v161, v71, v161
	v_exp_f32_e32 v76, v76
	v_add_f32_e32 v161, v72, v161
	v_exp_f32_e32 v77, v77
	v_add_f32_e32 v161, v73, v161
	v_exp_f32_e32 v78, v78
	v_add_f32_e32 v161, v74, v161
	v_exp_f32_e32 v79, v79
	v_add_f32_e32 v161, v75, v161
	v_add_f32_e32 v161, v76, v161
	v_add_f32_e32 v161, v77, v161
	v_add_f32_e32 v161, v78, v161
	v_add_f32_e32 v161, v79, v161
	v_add_f32_e32 v144, v144, v161
	v_cvt_pk_bf16_f32 v64, v64, v65
	v_cvt_pk_bf16_f32 v65, v66, v67
	v_cvt_pk_bf16_f32 v66, v68, v69
	v_cvt_pk_bf16_f32 v67, v70, v71
	v_cvt_pk_bf16_f32 v68, v72, v73
	v_cvt_pk_bf16_f32 v69, v74, v75
	v_cvt_pk_bf16_f32 v70, v76, v77
	v_cvt_pk_bf16_f32 v71, v78, v79
	s_nop 0
	v_permlane32_swap_b32_e32 v64, v66
	v_permlane32_swap_b32_e32 v65, v67
	v_permlane32_swap_b32_e32 v68, v70
	v_permlane32_swap_b32_e32 v69, v71
	s_waitcnt lgkmcnt(0)
	ds_read_b128 v[214:217], v167 offset:61440
	ds_read_b128 v[218:221], v168 offset:61440
	ds_read_b128 v[166:169], v169 offset:61440
	ds_read_b128 v[222:225], v170 offset:61440
	ds_read_b128 v[226:229], v171 offset:61440
	ds_read_b128 v[170:173], v172 offset:61440
	s_setprio 0
	v_mfma_f32_32x32x16_bf16 v[48:63], v[64:67], v[182:185], v[48:63]
	v_mfma_f32_32x32x16_bf16 v[32:47], v[64:67], v[190:193], v[32:47]
	v_mfma_f32_32x32x16_bf16 v[16:31], v[64:67], v[198:201], v[16:31]
	v_mfma_f32_32x32x16_bf16 v[0:15], v[64:67], v[206:209], v[0:15]
	v_mfma_f32_32x32x16_bf16 v[48:63], v[68:71], v[186:189], v[48:63]
	v_mfma_f32_32x32x16_bf16 v[32:47], v[68:71], v[194:197], v[32:47]
	v_mfma_f32_32x32x16_bf16 v[16:31], v[68:71], v[202:205], v[16:31]
	v_mfma_f32_32x32x16_bf16 v[0:15], v[68:71], v[210:213], v[0:15]
	s_waitcnt lgkmcnt(0)
	v_mfma_f32_32x32x16_bf16 v[64:79], v[132:135], v[80:83], 0
	v_mfma_f32_32x32x16_bf16 v[64:79], v[136:139], v[84:87], v[64:79]
	v_mfma_f32_32x32x16_bf16 v[64:79], v[140:143], v[88:91], v[64:79]
	v_mfma_f32_32x32x16_bf16 v[64:79], v[174:177], v[92:95], v[64:79]
	v_mfma_f32_32x32x16_bf16 v[64:79], v[162:165], v[96:99], v[64:79]
	v_mfma_f32_32x32x16_bf16 v[64:79], v[178:181], v[100:103], v[64:79]
	s_waitcnt lgkmcnt(0)
; #define LAS __attribute__((address_space(3)))
; DI void expsum(f32x16& p, float& l_reg, bf16x8& pa0, bf16x8& pa1) {
; #pragma unroll
;     for (int r = 0; r < 16; ++r) p[r] = __builtin_amdgcn_exp2f(p[r]);
;     float ps = 0.f;
; #pragma unroll
;     for (int r = 0; r < 16; ++r) ps += p[r];
;     l_reg += ps; asm volatile("" : "+v"(l_reg));
;     ...
;     ATT_PK4(p, 0, pa0); ATT_PK4(p, 8, pa1);
;     ...
; }
; DI int v_rd_base(int lane) { return ((lane & 3) << 3) | (((lane >> 2) & 3) << 6) | (((lane >> 4) & 1) << 5) | (((lane >> 5) & 1) << 8); }
; template <int OFF> DI s16x4 tr_read(int vb) { s16x4 r; asm volatile("ds_read_b64_tr_b16 %0, %1 offset:%2" : "=&v"(r) : "v"(vb), "i"(OFF) : "memory"); return r; }
; template <int H> DI void v_reads(s16x4* vf, int vb) {
;     vf[0] = tr_read<v_rd_off(0, 2 * H, 0)>(vb); vf[1] = tr_read<v_rd_off(0, 2 * H, 1)>(vb); vf[2] = tr_read<v_rd_off(0, 2 * H + 1, 0)>(vb); vf[3] = tr_read<v_rd_off(0, 2 * H + 1, 1)>(vb);
;     vf[4] = tr_read<v_rd_off(1, 2 * H, 0)>(vb); vf[5] = tr_read<v_rd_off(1, 2 * H, 1)>(vb); vf[6] = tr_read<v_rd_off(1, 2 * H + 1, 0)>(vb); vf[7] = tr_read<v_rd_off(1, 2 * H + 1, 1)>(vb);
;     vf[8] = tr_read<v_rd_off(2, 2 * H, 0)>(vb); vf[9] = tr_read<v_rd_off(2, 2 * H, 1)>(vb); vf[10] = tr_read<v_rd_off(2, 2 * H + 1, 0)>(vb); vf[11] = tr_read<v_rd_off(2, 2 * H + 1, 1)>(vb);
;     vf[12] = tr_read<v_rd_off(3, 2 * H, 0)>(vb); vf[13] = tr_read<v_rd_off(3, 2 * H, 1)>(vb); vf[14] = tr_read<v_rd_off(3, 2 * H + 1, 0)>(vb); vf[15] = tr_read<v_rd_off(3, 2 * H + 1, 1)>(vb);
; }
; DI void pv_mma(f32x16* o, const s16x4* vf, bf16x8 pa0, bf16x8 pa1) {
;     ...
; #pragma unroll
;     for (int d0 = 0; d0 < 4; ++d0) {
;         o[d0] = __builtin_amdgcn_mfma_f32_32x32x16_bf16(pa0, ATT_PK(vf[4 * d0], vf[4 * d0 + 1]), o[d0], 0, 0, 0);
;         o[d0] = __builtin_amdgcn_mfma_f32_32x32x16_bf16(pa1, ATT_PK(vf[4 * d0 + 2], vf[4 * d0 + 3]), o[d0], 0, 0, 0); }
;     ...
; }
; template <int DQK, int D0A, int D0B> DI void k_reads(bf16x8* kf, const LAS unsigned char* Ks, int half, int r32, int hi) {
; #pragma unroll
;     for (int d0 = D0A; d0 < D0B; ++d0) kf[d0 - D0A] = *(const LAS bf16x8*)(Ks + half * (32 * DQK * 2) + kswz<DQK>(r32, (d0 * 16 + hi * 8) * 2));
; }
; template <int D0A, int D0B> DI void qk_mma(f32x16& p, const bf16x8* kf, const bf16x8* qr) {
; #pragma unroll
;     for (int d0 = D0A; d0 < D0B; ++d0) {
	v_mfma_f32_32x32x16_bf16 v[64:79], v[214:217], v[104:107], v[64:79]
	v_mfma_f32_32x32x16_bf16 v[64:79], v[218:221], v[108:111], v[64:79]
	v_mfma_f32_32x32x16_bf16 v[64:79], v[166:169], v[112:115], v[64:79]
	v_mfma_f32_32x32x16_bf16 v[64:79], v[222:225], v[116:119], v[64:79]
	v_mfma_f32_32x32x16_bf16 v[64:79], v[226:229], v[120:123], v[64:79]
	v_mfma_f32_32x32x16_bf16 v[64:79], v[170:173], v[124:127], v[64:79]
	v_add_u32_e32 v158, 0x12000, v158
	v_add_u32_e32 v132, v158, v151
	v_add_u32_e32 v136, v158, v149
	v_add_u32_e32 v140, v158, v148
	v_add_u32_e32 v161, v158, v147
	ds_read_b128 v[132:135], v132
	ds_read_b128 v[136:139], v136
	ds_read_b128 v[140:143], v140
	ds_read_b128 v[162:165], v161
	v_add_u32_e32 v161, v158, v146
	v_add_u32_e32 v170, v158, v150
	ds_read_b128 v[166:169], v161
	ds_read_b128 v[170:173], v170
	ds_read_b64_tr_b16 v[174:175], v145 offset:0x2000
	ds_read_b64_tr_b16 v[176:177], v145 offset:0x2800
	ds_read_b64_tr_b16 v[178:179], v145 offset:0x3000
	ds_read_b64_tr_b16 v[180:181], v145 offset:0x3800
	ds_read_b64_tr_b16 v[182:183], v145 offset:0x2200
	ds_read_b64_tr_b16 v[184:185], v145 offset:0x2a00
	ds_read_b64_tr_b16 v[186:187], v145 offset:0x3200
	ds_read_b64_tr_b16 v[188:189], v145 offset:0x3a00
	ds_read_b64_tr_b16 v[190:191], v145 offset:0x2400
	ds_read_b64_tr_b16 v[192:193], v145 offset:0x2c00
	ds_read_b64_tr_b16 v[194:195], v145 offset:0x3400
	ds_read_b64_tr_b16 v[196:197], v145 offset:0x3c00
	ds_read_b64_tr_b16 v[198:199], v145 offset:0x2600
	ds_read_b64_tr_b16 v[200:201], v145 offset:0x2e00
	ds_read_b64_tr_b16 v[202:203], v145 offset:0x3600
	ds_read_b64_tr_b16 v[204:205], v145 offset:0x3e00
	s_setprio 1
	v_exp_f32_e32 v64, v64
	v_exp_f32_e32 v65, v65
	v_exp_f32_e32 v66, v66
	v_exp_f32_e32 v67, v67
	v_exp_f32_e32 v68, v68
	v_add_f32_e32 v145, 0, v64
	v_exp_f32_e32 v69, v69
	v_add_f32_e32 v145, v65, v145
	v_exp_f32_e32 v70, v70
	v_add_f32_e32 v145, v66, v145
	v_exp_f32_e32 v71, v71
	v_add_f32_e32 v145, v67, v145
	v_exp_f32_e32 v72, v72
	v_add_f32_e32 v145, v68, v145
	v_exp_f32_e32 v73, v73
	v_add_f32_e32 v145, v69, v145
	v_exp_f32_e32 v74, v74
	v_add_f32_e32 v145, v70, v145
	v_exp_f32_e32 v75, v75
	v_add_f32_e32 v145, v71, v145
	v_exp_f32_e32 v76, v76
	v_add_f32_e32 v145, v72, v145
	v_exp_f32_e32 v77, v77
	v_add_f32_e32 v145, v73, v145
	v_exp_f32_e32 v78, v78
	v_add_f32_e32 v145, v74, v145
	v_exp_f32_e32 v79, v79
	v_add_f32_e32 v145, v75, v145
	v_add_f32_e32 v145, v76, v145
	v_add_f32_e32 v145, v77, v145
	v_add_f32_e32 v145, v78, v145
	v_add_f32_e32 v145, v79, v145
	v_add_f32_e32 v161, v144, v145
	v_cvt_pk_bf16_f32 v64, v64, v65
	v_cvt_pk_bf16_f32 v65, v66, v67
	v_cvt_pk_bf16_f32 v66, v68, v69
	v_cvt_pk_bf16_f32 v67, v70, v71
	v_cvt_pk_bf16_f32 v68, v72, v73
	v_cvt_pk_bf16_f32 v69, v74, v75
	v_cvt_pk_bf16_f32 v70, v76, v77
	v_cvt_pk_bf16_f32 v71, v78, v79
	s_nop 0
	v_permlane32_swap_b32_e32 v64, v66
	v_permlane32_swap_b32_e32 v65, v67
	v_permlane32_swap_b32_e32 v68, v70
	v_permlane32_swap_b32_e32 v69, v71
	s_waitcnt lgkmcnt(0)
	v_add_u32_e32 v72, v158, v152
	v_add_u32_e32 v73, v158, v153
	ds_read_b128 v[206:209], v72
	ds_read_b128 v[210:213], v73
	v_add_u32_e32 v72, v158, v154
	v_add_u32_e32 v73, v158, v155
	ds_read_b128 v[214:217], v72
	ds_read_b128 v[218:221], v73
	v_add_u32_e32 v72, v158, v156
	v_add_u32_e32 v73, v158, v157
	ds_read_b128 v[222:225], v72
	ds_read_b128 v[226:229], v73
	s_setprio 0
	v_mfma_f32_32x32x16_bf16 v[48:63], v[64:67], v[174:177], v[48:63]
	v_mfma_f32_32x32x16_bf16 v[32:47], v[64:67], v[182:185], v[32:47]
	v_mfma_f32_32x32x16_bf16 v[16:31], v[64:67], v[190:193], v[16:31]
	v_mfma_f32_32x32x16_bf16 v[0:15], v[64:67], v[198:201], v[0:15]
	v_mfma_f32_32x32x16_bf16 v[48:63], v[68:71], v[178:181], v[48:63]
	v_mfma_f32_32x32x16_bf16 v[32:47], v[68:71], v[186:189], v[32:47]
	v_mfma_f32_32x32x16_bf16 v[16:31], v[68:71], v[194:197], v[16:31]
	v_mfma_f32_32x32x16_bf16 v[0:15], v[68:71], v[202:205], v[0:15]
	s_waitcnt lgkmcnt(0)
	v_mfma_f32_32x32x16_bf16 v[64:79], v[132:135], v[80:83], 0
	v_mfma_f32_32x32x16_bf16 v[64:79], v[136:139], v[84:87], v[64:79]
	v_mfma_f32_32x32x16_bf16 v[64:79], v[140:143], v[88:91], v[64:79]
	v_mfma_f32_32x32x16_bf16 v[64:79], v[162:165], v[92:95], v[64:79]
	v_mfma_f32_32x32x16_bf16 v[64:79], v[166:169], v[96:99], v[64:79]
	v_mfma_f32_32x32x16_bf16 v[64:79], v[170:173], v[100:103], v[64:79]
	s_waitcnt lgkmcnt(0)
	v_mfma_f32_32x32x16_bf16 v[64:79], v[206:209], v[104:107], v[64:79]
	v_mfma_f32_32x32x16_bf16 v[64:79], v[210:213], v[108:111], v[64:79]
	v_mfma_f32_32x32x16_bf16 v[64:79], v[214:217], v[112:115], v[64:79]
	v_mfma_f32_32x32x16_bf16 v[64:79], v[218:221], v[116:119], v[64:79]
	v_mfma_f32_32x32x16_bf16 v[64:79], v[222:225], v[120:123], v[64:79]
	v_mfma_f32_32x32x16_bf16 v[64:79], v[226:229], v[124:127], v[64:79]
	s_waitcnt vmcnt(0)
	s_barrier
; #define LAS __attribute__((address_space(3)))
; DI void expsum(f32x16& p, float& l_reg, bf16x8& pa0, bf16x8& pa1) {
; #pragma unroll
;     for (int r = 0; r < 16; ++r) p[r] = __builtin_amdgcn_exp2f(p[r]);
;     float ps = 0.f;
; #pragma unroll
;     for (int r = 0; r < 16; ++r) ps += p[r];
;     l_reg += ps; asm volatile("" : "+v"(l_reg));
;     ...
;     ATT_PK4(p, 0, pa0); ATT_PK4(p, 8, pa1);
;     ...
; }
; DI int v_rd_base(int lane) { return ((lane & 3) << 3) | (((lane >> 2) & 3) << 6) | (((lane >> 4) & 1) << 5) | (((lane >> 5) & 1) << 8); }
; template <int OFF> DI s16x4 tr_read(int vb) { s16x4 r; asm volatile("ds_read_b64_tr_b16 %0, %1 offset:%2" : "=&v"(r) : "v"(vb), "i"(OFF) : "memory"); return r; }
; template <int H> DI void v_reads(s16x4* vf, int vb) {
;     vf[0] = tr_read<v_rd_off(0, 2 * H, 0)>(vb); vf[1] = tr_read<v_rd_off(0, 2 * H, 1)>(vb); vf[2] = tr_read<v_rd_off(0, 2 * H + 1, 0)>(vb); vf[3] = tr_read<v_rd_off(0, 2 * H + 1, 1)>(vb);
;     vf[4] = tr_read<v_rd_off(1, 2 * H, 0)>(vb); vf[5] = tr_read<v_rd_off(1, 2 * H, 1)>(vb); vf[6] = tr_read<v_rd_off(1, 2 * H + 1, 0)>(vb); vf[7] = tr_read<v_rd_off(1, 2 * H + 1, 1)>(vb);
;     vf[8] = tr_read<v_rd_off(2, 2 * H, 0)>(vb); vf[9] = tr_read<v_rd_off(2, 2 * H, 1)>(vb); vf[10] = tr_read<v_rd_off(2, 2 * H + 1, 0)>(vb); vf[11] = tr_read<v_rd_off(2, 2 * H + 1, 1)>(vb);
;     vf[12] = tr_read<v_rd_off(3, 2 * H, 0)>(vb); vf[13] = tr_read<v_rd_off(3, 2 * H, 1)>(vb); vf[14] = tr_read<v_rd_off(3, 2 * H + 1, 0)>(vb); vf[15] = tr_read<v_rd_off(3, 2 * H + 1, 1)>(vb);
; }
; DI void pv_mma(f32x16* o, const s16x4* vf, bf16x8 pa0, bf16x8 pa1) {
;     ...
; #pragma unroll
;     for (int d0 = 0; d0 < 4; ++d0) {
;         o[d0] = __builtin_amdgcn_mfma_f32_32x32x16_bf16(pa0, ATT_PK(vf[4 * d0], vf[4 * d0 + 1]), o[d0], 0, 0, 0);
;         o[d0] = __builtin_amdgcn_mfma_f32_32x32x16_bf16(pa1, ATT_PK(vf[4 * d0 + 2], vf[4 * d0 + 3]), o[d0], 0, 0, 0); }
;     ...
; }
; template <int DQK, int D0A, int D0B> DI void k_reads(bf16x8* kf, const LAS unsigned char* Ks, int half, int r32, int hi) {
; #pragma unroll
;     for (int d0 = D0A; d0 < D0B; ++d0) kf[d0 - D0A] = *(const LAS bf16x8*)(Ks + half * (32 * DQK * 2) + kswz<DQK>(r32, (d0 * 16 + hi * 8) * 2));
; }
; template <int D0A, int D0B> DI void qk_mma(f32x16& p, const bf16x8* kf, const bf16x8* qr) {
; #pragma unroll
;     for (int d0 = D0A; d0 < D0B; ++d0) {
	v_add_u32_e32 v158, s82, v159
	v_add_u32_e32 v132, v158, v151
	v_add_u32_e32 v136, v158, v149
	v_add_u32_e32 v140, v158, v148
	v_add_u32_e32 v144, v158, v147
	ds_read_b128 v[132:135], v132
	ds_read_b128 v[136:139], v136
	ds_read_b128 v[140:143], v140
	ds_read_b128 v[162:165], v144
	v_add_u32_e32 v144, v158, v146
	v_add_u32_e32 v148, v158, v150
	ds_read_b128 v[144:147], v144
	ds_read_b128 v[148:151], v148
	ds_read_b64_tr_b16 v[166:167], v130 offset:0
	ds_read_b64_tr_b16 v[168:169], v130 offset:0x800
	ds_read_b64_tr_b16 v[170:171], v130 offset:0x1000
	ds_read_b64_tr_b16 v[172:173], v130 offset:0x1800
	ds_read_b64_tr_b16 v[174:175], v130 offset:0x200
	ds_read_b64_tr_b16 v[176:177], v130 offset:0xa00
	ds_read_b64_tr_b16 v[178:179], v130 offset:0x1200
	ds_read_b64_tr_b16 v[180:181], v130 offset:0x1a00
	ds_read_b64_tr_b16 v[182:183], v130 offset:0x400
	ds_read_b64_tr_b16 v[184:185], v130 offset:0xc00
	ds_read_b64_tr_b16 v[186:187], v130 offset:0x1400
	ds_read_b64_tr_b16 v[188:189], v130 offset:0x1c00
	ds_read_b64_tr_b16 v[190:191], v130 offset:0x600
	ds_read_b64_tr_b16 v[192:193], v130 offset:0xe00
	ds_read_b64_tr_b16 v[194:195], v130 offset:0x1600
	ds_read_b64_tr_b16 v[196:197], v130 offset:0x1e00
	s_setprio 1
	v_exp_f32_e32 v64, v64
	v_exp_f32_e32 v65, v65
	v_exp_f32_e32 v66, v66
	v_exp_f32_e32 v67, v67
	v_exp_f32_e32 v68, v68
	v_add_f32_e32 v159, 0, v64
	v_exp_f32_e32 v69, v69
	v_add_f32_e32 v159, v65, v159
	v_exp_f32_e32 v70, v70
	v_add_f32_e32 v159, v66, v159
	v_exp_f32_e32 v71, v71
	v_add_f32_e32 v159, v67, v159
	v_exp_f32_e32 v72, v72
	v_add_f32_e32 v159, v68, v159
	v_exp_f32_e32 v73, v73
	v_add_f32_e32 v159, v69, v159
	v_exp_f32_e32 v74, v74
	v_add_f32_e32 v159, v70, v159
	v_exp_f32_e32 v75, v75
	v_add_f32_e32 v159, v71, v159
	v_exp_f32_e32 v76, v76
	v_add_f32_e32 v159, v72, v159
	v_exp_f32_e32 v77, v77
	v_add_f32_e32 v159, v73, v159
	v_exp_f32_e32 v78, v78
	v_add_f32_e32 v159, v74, v159
	v_exp_f32_e32 v79, v79
	v_add_f32_e32 v159, v75, v159
	v_add_f32_e32 v159, v76, v159
	v_add_f32_e32 v159, v77, v159
	v_add_f32_e32 v159, v78, v159
	v_add_f32_e32 v159, v79, v159
	v_add_f32_e32 v161, v161, v159
	v_cvt_pk_bf16_f32 v64, v64, v65
	v_cvt_pk_bf16_f32 v65, v66, v67
	v_cvt_pk_bf16_f32 v66, v68, v69
	v_cvt_pk_bf16_f32 v67, v70, v71
	v_cvt_pk_bf16_f32 v68, v72, v73
	v_cvt_pk_bf16_f32 v69, v74, v75
	v_cvt_pk_bf16_f32 v70, v76, v77
	v_cvt_pk_bf16_f32 v71, v78, v79
	s_nop 0
	v_permlane32_swap_b32_e32 v64, v66
	v_permlane32_swap_b32_e32 v65, v67
	v_permlane32_swap_b32_e32 v68, v70
	v_permlane32_swap_b32_e32 v69, v71
	s_waitcnt lgkmcnt(0)
	v_add_u32_e32 v72, v158, v152
	v_add_u32_e32 v73, v158, v153
	ds_read_b128 v[198:201], v72
	ds_read_b128 v[202:205], v73
	v_add_u32_e32 v72, v158, v154
	v_add_u32_e32 v73, v158, v155
	ds_read_b128 v[152:155], v72
	ds_read_b128 v[206:209], v73
	v_add_u32_e32 v72, v158, v156
	v_add_u32_e32 v73, v158, v157
	ds_read_b128 v[156:159], v72
	ds_read_b128 v[210:213], v73
	s_setprio 0
	v_mfma_f32_32x32x16_bf16 v[48:63], v[64:67], v[166:169], v[48:63]
	v_mfma_f32_32x32x16_bf16 v[32:47], v[64:67], v[174:177], v[32:47]
	v_mfma_f32_32x32x16_bf16 v[16:31], v[64:67], v[182:185], v[16:31]
	v_mfma_f32_32x32x16_bf16 v[0:15], v[64:67], v[190:193], v[0:15]
	v_mfma_f32_32x32x16_bf16 v[48:63], v[68:71], v[170:173], v[48:63]
	v_mfma_f32_32x32x16_bf16 v[32:47], v[68:71], v[178:181], v[32:47]
	v_mfma_f32_32x32x16_bf16 v[16:31], v[68:71], v[186:189], v[16:31]
	v_mfma_f32_32x32x16_bf16 v[0:15], v[68:71], v[194:197], v[0:15]
	s_waitcnt lgkmcnt(0)
; template <int TAG = 0> DI int fresh_tid(int wv) { int l; asm volatile("v_mbcnt_lo_u32_b32 %0, -1, 0\n\tv_mbcnt_hi_u32_b32 %0, -1, %0 ; site %1" : "=v"(l) : "n"(TAG)); return wv * 64 + l; }
; DI void expsum(f32x16& p, float& l_reg, bf16x8& pa0, bf16x8& pa1) {
; #pragma unroll
;     for (int r = 0; r < 16; ++r) p[r] = __builtin_amdgcn_exp2f(p[r]);
;     float ps = 0.f;
; #pragma unroll
;     for (int r = 0; r < 16; ++r) ps += p[r];
;     l_reg += ps; asm volatile("" : "+v"(l_reg));
;     ...
;     ATT_PK4(p, 0, pa0); ATT_PK4(p, 8, pa1);
;     ...
; }
; DI int v_rd_base(int lane) { return ((lane & 3) << 3) | (((lane >> 2) & 3) << 6) | (((lane >> 4) & 1) << 5) | (((lane >> 5) & 1) << 8); }
; template <int OFF> DI s16x4 tr_read(int vb) { s16x4 r; asm volatile("ds_read_b64_tr_b16 %0, %1 offset:%2" : "=&v"(r) : "v"(vb), "i"(OFF) : "memory"); return r; }
; template <int H> DI void v_reads(s16x4* vf, int vb) {
;     vf[0] = tr_read<v_rd_off(0, 2 * H, 0)>(vb); vf[1] = tr_read<v_rd_off(0, 2 * H, 1)>(vb); vf[2] = tr_read<v_rd_off(0, 2 * H + 1, 0)>(vb); vf[3] = tr_read<v_rd_off(0, 2 * H + 1, 1)>(vb);
;     vf[4] = tr_read<v_rd_off(1, 2 * H, 0)>(vb); vf[5] = tr_read<v_rd_off(1, 2 * H, 1)>(vb); vf[6] = tr_read<v_rd_off(1, 2 * H + 1, 0)>(vb); vf[7] = tr_read<v_rd_off(1, 2 * H + 1, 1)>(vb);
;     vf[8] = tr_read<v_rd_off(2, 2 * H, 0)>(vb); vf[9] = tr_read<v_rd_off(2, 2 * H, 1)>(vb); vf[10] = tr_read<v_rd_off(2, 2 * H + 1, 0)>(vb); vf[11] = tr_read<v_rd_off(2, 2 * H + 1, 1)>(vb);
;     vf[12] = tr_read<v_rd_off(3, 2 * H, 0)>(vb); vf[13] = tr_read<v_rd_off(3, 2 * H, 1)>(vb); vf[14] = tr_read<v_rd_off(3, 2 * H + 1, 0)>(vb); vf[15] = tr_read<v_rd_off(3, 2 * H + 1, 1)>(vb);
; }
; DI void pv_mma(f32x16* o, const s16x4* vf, bf16x8 pa0, bf16x8 pa1) {
;     ...
; #pragma unroll
;     for (int d0 = 0; d0 < 4; ++d0) {
;         o[d0] = __builtin_amdgcn_mfma_f32_32x32x16_bf16(pa0, ATT_PK(vf[4 * d0], vf[4 * d0 + 1]), o[d0], 0, 0, 0);
;         o[d0] = __builtin_amdgcn_mfma_f32_32x32x16_bf16(pa1, ATT_PK(vf[4 * d0 + 2], vf[4 * d0 + 3]), o[d0], 0, 0, 0); }
;     ...
; }
; template <int DQK, int MODE, int LDQ, int LDK, int LDV> ...
;     ...
;     l_reg = swap_sum(l_reg);
;     { const int lane2 = fresh_tid<110 + MODE>(wv) & 63, r32 = lane2 & 31, hi = lane2 >> 5;
;     if (hi == 0) li_l[r32] = l_reg;
	v_mfma_f32_32x32x16_bf16 v[64:79], v[132:135], v[80:83], 0
	v_mfma_f32_32x32x16_bf16 v[64:79], v[136:139], v[84:87], v[64:79]
	v_mfma_f32_32x32x16_bf16 v[64:79], v[140:143], v[88:91], v[64:79]
	v_mfma_f32_32x32x16_bf16 v[64:79], v[162:165], v[92:95], v[64:79]
	v_mfma_f32_32x32x16_bf16 v[64:79], v[144:147], v[96:99], v[64:79]
	v_mfma_f32_32x32x16_bf16 v[64:79], v[148:151], v[100:103], v[64:79]
	s_waitcnt lgkmcnt(0)
	v_mfma_f32_32x32x16_bf16 v[64:79], v[198:201], v[104:107], v[64:79]
	v_mfma_f32_32x32x16_bf16 v[64:79], v[202:205], v[108:111], v[64:79]
	v_mfma_f32_32x32x16_bf16 v[64:79], v[152:155], v[112:115], v[64:79]
	v_mfma_f32_32x32x16_bf16 v[64:79], v[206:209], v[116:119], v[64:79]
	v_mfma_f32_32x32x16_bf16 v[64:79], v[156:159], v[120:123], v[64:79]
	v_mfma_f32_32x32x16_bf16 v[64:79], v[210:213], v[124:127], v[64:79]
	ds_read_b64_tr_b16 v[80:81], v130 offset:0x2000
	ds_read_b64_tr_b16 v[82:83], v130 offset:0x2800
	ds_read_b64_tr_b16 v[84:85], v130 offset:0x3000
	ds_read_b64_tr_b16 v[86:87], v130 offset:0x3800
	ds_read_b64_tr_b16 v[88:89], v130 offset:0x2200
	ds_read_b64_tr_b16 v[90:91], v130 offset:0x2a00
	ds_read_b64_tr_b16 v[92:93], v130 offset:0x3200
	ds_read_b64_tr_b16 v[94:95], v130 offset:0x3a00
	ds_read_b64_tr_b16 v[96:97], v130 offset:0x2400
	ds_read_b64_tr_b16 v[98:99], v130 offset:0x2c00
	ds_read_b64_tr_b16 v[100:101], v130 offset:0x3400
	ds_read_b64_tr_b16 v[102:103], v130 offset:0x3c00
	ds_read_b64_tr_b16 v[104:105], v130 offset:0x2600
	ds_read_b64_tr_b16 v[106:107], v130 offset:0x2e00
	ds_read_b64_tr_b16 v[108:109], v130 offset:0x3600
	ds_read_b64_tr_b16 v[110:111], v130 offset:0x3e00
	s_nop 11
	s_setprio 1
	v_exp_f32_e32 v112, v64
	v_exp_f32_e32 v65, v65
	v_exp_f32_e32 v113, v66
	v_exp_f32_e32 v67, v67
	v_exp_f32_e32 v68, v68
	v_add_f32_e32 v64, 0, v112
	v_exp_f32_e32 v69, v69
	v_add_f32_e32 v64, v65, v64
	v_exp_f32_e32 v70, v70
	v_add_f32_e32 v64, v113, v64
	v_exp_f32_e32 v71, v71
	v_add_f32_e32 v64, v67, v64
	v_exp_f32_e32 v72, v72
	v_add_f32_e32 v64, v68, v64
	v_exp_f32_e32 v73, v73
	v_add_f32_e32 v64, v69, v64
	v_exp_f32_e32 v74, v74
	v_add_f32_e32 v64, v70, v64
	v_exp_f32_e32 v75, v75
	v_add_f32_e32 v64, v71, v64
	v_exp_f32_e32 v76, v76
	v_add_f32_e32 v64, v72, v64
	v_exp_f32_e32 v77, v77
	v_add_f32_e32 v64, v73, v64
	v_exp_f32_e32 v78, v78
	v_add_f32_e32 v64, v74, v64
	v_exp_f32_e32 v79, v79
	v_add_f32_e32 v64, v75, v64
	v_add_f32_e32 v64, v76, v64
	v_add_f32_e32 v64, v77, v64
	v_add_f32_e32 v64, v78, v64
	v_add_f32_e32 v64, v79, v64
	v_add_f32_e32 v64, v161, v64
	v_cvt_pk_bf16_f32 v66, v112, v65
	v_cvt_pk_bf16_f32 v67, v113, v67
	v_cvt_pk_bf16_f32 v68, v68, v69
	v_cvt_pk_bf16_f32 v69, v70, v71
	v_cvt_pk_bf16_f32 v70, v72, v73
	v_cvt_pk_bf16_f32 v71, v74, v75
	v_cvt_pk_bf16_f32 v72, v76, v77
	v_cvt_pk_bf16_f32 v73, v78, v79
	s_nop 0
	v_permlane32_swap_b32_e32 v66, v68
	v_permlane32_swap_b32_e32 v67, v69
	v_permlane32_swap_b32_e32 v70, v72
	v_permlane32_swap_b32_e32 v71, v73
	s_waitcnt lgkmcnt(0)
	s_setprio 0
	v_mfma_f32_32x32x16_bf16 v[48:63], v[66:69], v[80:83], v[48:63]
	v_mfma_f32_32x32x16_bf16 v[32:47], v[66:69], v[88:91], v[32:47]
	v_mfma_f32_32x32x16_bf16 v[16:31], v[66:69], v[96:99], v[16:31]
	v_mfma_f32_32x32x16_bf16 v[0:15], v[66:69], v[104:107], v[0:15]
	v_mfma_f32_32x32x16_bf16 v[48:63], v[70:73], v[84:87], v[48:63]
	v_mfma_f32_32x32x16_bf16 v[32:47], v[70:73], v[92:95], v[32:47]
	v_mfma_f32_32x32x16_bf16 v[16:31], v[70:73], v[100:103], v[16:31]
	v_mfma_f32_32x32x16_bf16 v[0:15], v[70:73], v[108:111], v[0:15]
	s_setprio 0
	v_mbcnt_lo_u32_b32 v66, -1, 0
	v_mbcnt_hi_u32_b32 v66, -1, v66
	v_mov_b32_e32 v67, v64
	v_and_b32_e32 v65, 31, v66
	v_bfe_u32 v66, v66, 5, 1
	v_permlane32_swap_b32_e32 v64, v67
	v_cmp_eq_u32_e32 vcc, 0, v66
	s_and_saveexec_b64 s[2:3], vcc
	s_cbranch_execz .LBB0_1910
	v_lshl_add_u32 v68, v65, 2, s4
	v_add_f32_e32 v64, v64, v67
	ds_write_b32 v68, v64
	s_branch .LBB0_1910
